# gdn gate (phase 4) rewritten: all rows requested up front and each 1 KiB half of a token row accessed lane-contiguously
# speedup vs baseline: 1.0167x; 1.0059x over previous
; DI void phase_gdn_gate(const Params& p) {
;     const int lane = threadIdx.x & 63, gw = blockIdx.x * 8 + (threadIdx.x >> 6), nw = gridDim.x * 8;
;     const bf16_t* oraw = (const bf16_t*)(p.ws + WS_ORAW); const bf16_t* P0 = (const bf16_t*)(p.ws + WS_P0); bf16_t* og = (bf16_t*)(p.ws + WS_OG);
;     for (int tok = gw; tok < T_TOK; tok += nw) {
;         const u32x4 a0 = *(const u32x4*)(oraw + (size_t)tok * 1024 + 16 * lane), a1 = *(const u32x4*)(oraw + (size_t)tok * 1024 + 16 * lane + 8);
;         const u32x4 z0 = *(const u32x4*)(P0 + (size_t)tok * LDP0 + 3072 + 16 * lane), z1 = *(const u32x4*)(P0 + (size_t)tok * LDP0 + 3072 + 16 * lane + 8);
.LBB0_930:
	s_cmp_lt_i32 s80, 5
	s_cselect_b64 s[4:5], -1, 0
	v_add_u32_e32 v162, s83, v155
	s_movk_i32 s3, 0x4400
	s_and_b64 s[0:1], s[4:5], s[0:1]
	v_cmp_gt_i32_e64 s[44:45], s3, v162
	s_lshl_b32 s46, s94, 3
	s_and_b64 s[0:1], s[44:45], s[0:1]
	v_ashrrev_i32_e32 v163, 31, v162
	v_mbcnt_lo_u32_b32 v197, -1, 0
	v_and_b32_e32 v196, 63, v1
	s_and_saveexec_b64 s[6:7], s[0:1]
	s_cbranch_execz .LBB0_933
	v_readlane_b32 s14, v238, 6
	v_readlane_b32 s15, v238, 7
	v_lshlrev_b32_e32 v2, 4, v196
	v_and_b32_e32 v3, 15, v196
	v_lshlrev_b32_e32 v3, 5, v3
	s_add_u32 s10, s78, 0x3c80000
	s_addc_u32 s11, s79, 0
	s_add_u32 s12, s78, 0x1d481800
	s_addc_u32 s13, s79, 0
	s_add_u32 s16, s78, 0x8080000
	s_addc_u32 s17, s79, 0
	v_readfirstlane_b32 s8, v162
	v_mov_b32_e32 v15, 0x358637bd
	s_cmpk_lt_u32 s8, 0x400
	s_cbranch_scc0 .Lg4_no9a
	s_mul_i32 s9, s46, 8
	s_add_i32 s9, s9, s8
	s_lshl_b32 s3, s9, 11
	s_add_u32 s20, s10, s3
	s_addc_u32 s21, s11, 0
	s_mul_i32 s3, s9, 0x2200
	s_add_u32 s22, s12, s3
	s_addc_u32 s23, s13, 0
	global_load_dwordx4 v[198:201], v2, s[20:21]
	global_load_dwordx4 v[202:205], v2, s[20:21] offset:1024
	global_load_dwordx4 v[206:209], v2, s[22:23]
	global_load_dwordx4 v[210:213], v2, s[22:23] offset:1024
.Lg4_no9a:
	global_load_dwordx4 v[16:19], v3, s[14:15]
	global_load_dwordx4 v[20:23], v3, s[14:15] offset:16
	global_load_dwordx4 v[24:27], v3, s[14:15]
	global_load_dwordx4 v[28:31], v3, s[14:15] offset:16
	s_mul_i32 s9, s46, 0
	s_add_i32 s9, s9, s8
	s_lshl_b32 s3, s9, 11
	s_add_u32 s20, s10, s3
	s_addc_u32 s21, s11, 0
	s_mul_i32 s3, s9, 0x2200
	s_add_u32 s22, s12, s3
	s_addc_u32 s23, s13, 0
	global_load_dwordx4 v[32:35], v2, s[20:21]
	global_load_dwordx4 v[36:39], v2, s[20:21] offset:1024
	global_load_dwordx4 v[40:43], v2, s[22:23]
	global_load_dwordx4 v[44:47], v2, s[22:23] offset:1024
	s_mul_i32 s9, s46, 1
	s_add_i32 s9, s9, s8
	s_lshl_b32 s3, s9, 11
	s_add_u32 s20, s10, s3
	s_addc_u32 s21, s11, 0
	s_mul_i32 s3, s9, 0x2200
	s_add_u32 s22, s12, s3
	s_addc_u32 s23, s13, 0
	global_load_dwordx4 v[48:51], v2, s[20:21]
	global_load_dwordx4 v[52:55], v2, s[20:21] offset:1024
	global_load_dwordx4 v[56:59], v2, s[22:23]
	global_load_dwordx4 v[60:63], v2, s[22:23] offset:1024
	s_mul_i32 s9, s46, 2
	s_add_i32 s9, s9, s8
	s_lshl_b32 s3, s9, 11
	s_add_u32 s20, s10, s3
	s_addc_u32 s21, s11, 0
	s_mul_i32 s3, s9, 0x2200
	s_add_u32 s22, s12, s3
	s_addc_u32 s23, s13, 0
	global_load_dwordx4 v[64:67], v2, s[20:21]
	global_load_dwordx4 v[68:71], v2, s[20:21] offset:1024
	global_load_dwordx4 v[72:75], v2, s[22:23]
	global_load_dwordx4 v[76:79], v2, s[22:23] offset:1024
	s_mul_i32 s9, s46, 3
	s_add_i32 s9, s9, s8
	s_lshl_b32 s3, s9, 11
	s_add_u32 s20, s10, s3
	s_addc_u32 s21, s11, 0
	s_mul_i32 s3, s9, 0x2200
	s_add_u32 s22, s12, s3
	s_addc_u32 s23, s13, 0
	global_load_dwordx4 v[80:83], v2, s[20:21]
	global_load_dwordx4 v[84:87], v2, s[20:21] offset:1024
	global_load_dwordx4 v[88:91], v2, s[22:23]
	global_load_dwordx4 v[92:95], v2, s[22:23] offset:1024
	s_mul_i32 s9, s46, 4
	s_add_i32 s9, s9, s8
	s_lshl_b32 s3, s9, 11
	s_add_u32 s20, s10, s3
	s_addc_u32 s21, s11, 0
	s_mul_i32 s3, s9, 0x2200
	s_add_u32 s22, s12, s3
	s_addc_u32 s23, s13, 0
	global_load_dwordx4 v[96:99], v2, s[20:21]
	global_load_dwordx4 v[100:103], v2, s[20:21] offset:1024
	global_load_dwordx4 v[104:107], v2, s[22:23]
	global_load_dwordx4 v[108:111], v2, s[22:23] offset:1024
	s_mul_i32 s9, s46, 5
	s_add_i32 s9, s9, s8
	s_lshl_b32 s3, s9, 11
	s_add_u32 s20, s10, s3
	s_addc_u32 s21, s11, 0
	s_mul_i32 s3, s9, 0x2200
	s_add_u32 s22, s12, s3
	s_addc_u32 s23, s13, 0
	global_load_dwordx4 v[112:115], v2, s[20:21]
	global_load_dwordx4 v[116:119], v2, s[20:21] offset:1024
	global_load_dwordx4 v[120:123], v2, s[22:23]
	global_load_dwordx4 v[124:127], v2, s[22:23] offset:1024
	s_mul_i32 s9, s46, 6
	s_add_i32 s9, s9, s8
	s_lshl_b32 s3, s9, 11
	s_add_u32 s20, s10, s3
	s_addc_u32 s21, s11, 0
	s_mul_i32 s3, s9, 0x2200
	s_add_u32 s22, s12, s3
	s_addc_u32 s23, s13, 0
	global_load_dwordx4 v[128:131], v2, s[20:21]
	global_load_dwordx4 v[132:135], v2, s[20:21] offset:1024
	global_load_dwordx4 v[136:139], v2, s[22:23]
	global_load_dwordx4 v[140:143], v2, s[22:23] offset:1024
	s_mul_i32 s9, s46, 7
	s_add_i32 s9, s9, s8
	s_lshl_b32 s3, s9, 11
	s_add_u32 s20, s10, s3
	s_addc_u32 s21, s11, 0
	s_mul_i32 s3, s9, 0x2200
	s_add_u32 s22, s12, s3
	s_addc_u32 s23, s13, 0
	global_load_dwordx4 v[168:171], v2, s[20:21]
	global_load_dwordx4 v[172:175], v2, s[20:21] offset:1024
	global_load_dwordx4 v[176:179], v2, s[22:23]
	global_load_dwordx4 v[180:183], v2, s[22:23] offset:1024
	s_waitcnt vmcnt(28)
; DI unsigned pk_bf16(float a, float b) { f32x2 v = {a, b}; bf2_t r = __builtin_convertvector(v, bf2_t); return __builtin_bit_cast(unsigned, r); }
; DI float bflo(unsigned u) { return __uint_as_float(u << 16); }
; DI float bfhi(unsigned u) { return __uint_as_float(u & 0xffff0000u); }
; DI float silu_f(float x) { return x * __builtin_amdgcn_rcpf(1.f + __expf(-x)); }
; DI void phase_gdn_gate(const Params& p) {
;     ...
;         const u32x4 z0 = *(const u32x4*)(P0 + (size_t)tok * LDP0 + 3072 + 16 * lane), z1 = *(const u32x4*)(P0 + (size_t)tok * LDP0 + 3072 + 16 * lane + 8);
;         float o[16], z[16];
;         const unsigned au[8] = {a0.x, a0.y, a0.z, a0.w, a1.x, a1.y, a1.z, a1.w}, zu[8] = {z0.x, z0.y, z0.z, z0.w, z1.x, z1.y, z1.z, z1.w};
;         float ss = 0.f;
; #pragma unroll
;         for (int i = 0; i < 8; ++i) { o[2 * i] = bflo(au[i]); o[2 * i + 1] = bfhi(au[i]); z[2 * i] = bflo(zu[i]); z[2 * i + 1] = bfhi(zu[i]); ss += o[2 * i] * o[2 * i] + o[2 * i + 1] * o[2 * i + 1]; }
;         ss += __shfl_xor(ss, 1); ss += __shfl_xor(ss, 2); ss += __shfl_xor(ss, 4);
;         const float rstd = rsqrtf(ss * (1.f / 128.f) + 1e-6f);
;         const int d0 = (16 * lane) & 127;
;         unsigned r[8];
; #pragma unroll
;         for (int i = 0; i < 8; ++i) { const float v0 = o[2 * i] * rstd * p.onorm_a[d0 + 2 * i] * silu_f(z[2 * i]), v1 = o[2 * i + 1] * rstd * p.onorm_a[d0 + 2 * i + 1] * silu_f(z[2 * i + 1]); r[i] = pk_bf16(v0, v1); }
;         *(u32x4*)(og + (size_t)tok * 1024 + 16 * lane) = (u32x4){r[0], r[1], r[2], r[3]};
;         *(u32x4*)(og + (size_t)tok * 1024 + 16 * lane + 8) = (u32x4){r[4], r[5], r[6], r[7]};
	v_lshlrev_b32_e32 v214, 16, v32
	v_and_b32_e32 v215, 0xffff0000, v32
	v_lshlrev_b32_e32 v216, 16, v33
	v_and_b32_e32 v217, 0xffff0000, v33
	v_lshlrev_b32_e32 v218, 16, v34
	v_and_b32_e32 v219, 0xffff0000, v34
	v_lshlrev_b32_e32 v220, 16, v35
	v_and_b32_e32 v221, 0xffff0000, v35
	v_lshlrev_b32_e32 v222, 16, v36
	v_and_b32_e32 v223, 0xffff0000, v36
	v_lshlrev_b32_e32 v224, 16, v37
	v_and_b32_e32 v225, 0xffff0000, v37
	v_lshlrev_b32_e32 v226, 16, v38
	v_and_b32_e32 v227, 0xffff0000, v38
	v_lshlrev_b32_e32 v228, 16, v39
	v_and_b32_e32 v229, 0xffff0000, v39
	v_mul_f32_e32 v144, v214, v214
	v_fmac_f32_e32 v144, v215, v215
	v_fmac_f32_e32 v144, v216, v216
	v_fmac_f32_e32 v144, v217, v217
	v_fmac_f32_e32 v144, v218, v218
	v_fmac_f32_e32 v144, v219, v219
	v_fmac_f32_e32 v144, v220, v220
	v_fmac_f32_e32 v144, v221, v221
	v_mul_f32_e32 v145, v222, v222
	v_fmac_f32_e32 v145, v223, v223
	v_fmac_f32_e32 v145, v224, v224
	v_fmac_f32_e32 v145, v225, v225
	v_fmac_f32_e32 v145, v226, v226
	v_fmac_f32_e32 v145, v227, v227
	v_fmac_f32_e32 v145, v228, v228
	v_fmac_f32_e32 v145, v229, v229
	v_lshlrev_b32_e32 v240, 16, v40
	v_and_b32_e32 v241, 0xffff0000, v40
	v_lshlrev_b32_e32 v242, 16, v41
	v_and_b32_e32 v243, 0xffff0000, v41
	v_lshlrev_b32_e32 v244, 16, v42
	v_and_b32_e32 v245, 0xffff0000, v42
	v_lshlrev_b32_e32 v246, 16, v43
	v_and_b32_e32 v247, 0xffff0000, v43
	v_lshlrev_b32_e32 v248, 16, v44
	v_and_b32_e32 v249, 0xffff0000, v44
	v_lshlrev_b32_e32 v250, 16, v45
	v_and_b32_e32 v251, 0xffff0000, v45
	v_lshlrev_b32_e32 v252, 16, v46
	v_and_b32_e32 v253, 0xffff0000, v46
	v_lshlrev_b32_e32 v254, 16, v47
	v_and_b32_e32 v255, 0xffff0000, v47
	s_nop 1
	v_add_f32_dpp v144, v144, v144 quad_perm:[1,0,3,2] row_mask:0xf bank_mask:0xf
	v_add_f32_dpp v145, v145, v145 quad_perm:[1,0,3,2] row_mask:0xf bank_mask:0xf
	s_nop 1
	v_add_f32_dpp v144, v144, v144 quad_perm:[2,3,0,1] row_mask:0xf bank_mask:0xf
	v_add_f32_dpp v145, v145, v145 quad_perm:[2,3,0,1] row_mask:0xf bank_mask:0xf
	s_nop 1
	v_add_f32_dpp v144, v144, v144 row_ror:4 row_mask:0xf bank_mask:0xf
	v_add_f32_dpp v145, v145, v145 row_ror:4 row_mask:0xf bank_mask:0xf
	s_nop 1
	v_add_f32_dpp v144, v144, v144 row_ror:8 row_mask:0xf bank_mask:0xf
	v_add_f32_dpp v145, v145, v145 row_ror:8 row_mask:0xf bank_mask:0xf
	v_fmamk_f32 v144, v144, 0x3c000000, v15
	v_fmamk_f32 v145, v145, 0x3c000000, v15
	v_rsq_f32_e32 v144, v144
	v_rsq_f32_e32 v145, v145
	v_mul_f32_e32 v148, 0xbfb8aa3b, v240
	v_mul_f32_e32 v149, 0xbfb8aa3b, v241
	v_mul_f32_e32 v150, 0xbfb8aa3b, v242
	v_mul_f32_e32 v151, 0xbfb8aa3b, v243
	v_mul_f32_e32 v4, 0xbfb8aa3b, v244
	v_mul_f32_e32 v5, 0xbfb8aa3b, v245
	v_mul_f32_e32 v6, 0xbfb8aa3b, v246
	v_mul_f32_e32 v7, 0xbfb8aa3b, v247
	v_exp_f32_e32 v148, v148
	v_exp_f32_e32 v149, v149
	v_exp_f32_e32 v150, v150
	v_exp_f32_e32 v151, v151
	v_exp_f32_e32 v4, v4
	v_exp_f32_e32 v5, v5
	v_exp_f32_e32 v6, v6
	v_exp_f32_e32 v7, v7
	v_add_f32_e32 v148, 1.0, v148
	v_add_f32_e32 v149, 1.0, v149
	v_add_f32_e32 v150, 1.0, v150
	v_add_f32_e32 v151, 1.0, v151
	v_add_f32_e32 v4, 1.0, v4
	v_add_f32_e32 v5, 1.0, v5
	v_add_f32_e32 v6, 1.0, v6
	v_add_f32_e32 v7, 1.0, v7
	v_rcp_f32_e32 v148, v148
	v_rcp_f32_e32 v149, v149
	v_rcp_f32_e32 v150, v150
	v_rcp_f32_e32 v151, v151
	v_rcp_f32_e32 v4, v4
	v_rcp_f32_e32 v5, v5
	v_rcp_f32_e32 v6, v6
	v_rcp_f32_e32 v7, v7
	v_mul_f32_e32 v240, v148, v240
	v_mul_f32_e32 v241, v149, v241
	v_mul_f32_e32 v242, v150, v242
	v_mul_f32_e32 v243, v151, v243
	v_mul_f32_e32 v244, v4, v244
	v_mul_f32_e32 v245, v5, v245
	v_mul_f32_e32 v246, v6, v246
	v_mul_f32_e32 v247, v7, v247
	v_mul_f32_e32 v148, 0xbfb8aa3b, v248
	v_mul_f32_e32 v149, 0xbfb8aa3b, v249
	v_mul_f32_e32 v150, 0xbfb8aa3b, v250
	v_mul_f32_e32 v151, 0xbfb8aa3b, v251
	v_mul_f32_e32 v4, 0xbfb8aa3b, v252
	v_mul_f32_e32 v5, 0xbfb8aa3b, v253
	v_mul_f32_e32 v6, 0xbfb8aa3b, v254
	v_mul_f32_e32 v7, 0xbfb8aa3b, v255
	v_exp_f32_e32 v148, v148
	v_exp_f32_e32 v149, v149
	v_exp_f32_e32 v150, v150
	v_exp_f32_e32 v151, v151
	v_exp_f32_e32 v4, v4
	v_exp_f32_e32 v5, v5
	v_exp_f32_e32 v6, v6
	v_exp_f32_e32 v7, v7
	v_add_f32_e32 v148, 1.0, v148
	v_add_f32_e32 v149, 1.0, v149
	v_add_f32_e32 v150, 1.0, v150
	v_add_f32_e32 v151, 1.0, v151
	v_add_f32_e32 v4, 1.0, v4
	v_add_f32_e32 v5, 1.0, v5
	v_add_f32_e32 v6, 1.0, v6
	v_add_f32_e32 v7, 1.0, v7
	v_rcp_f32_e32 v148, v148
	v_rcp_f32_e32 v149, v149
	v_rcp_f32_e32 v150, v150
	v_rcp_f32_e32 v151, v151
	v_rcp_f32_e32 v4, v4
	v_rcp_f32_e32 v5, v5
	v_rcp_f32_e32 v6, v6
	v_rcp_f32_e32 v7, v7
	v_mul_f32_e32 v248, v148, v248
	v_mul_f32_e32 v249, v149, v249
	v_mul_f32_e32 v250, v150, v250
	v_mul_f32_e32 v251, v151, v251
	v_mul_f32_e32 v252, v4, v252
	v_mul_f32_e32 v253, v5, v253
	v_mul_f32_e32 v254, v6, v254
	v_mul_f32_e32 v255, v7, v255
	v_mul_f32_e32 v214, v144, v214
	v_mul_f32_e32 v215, v144, v215
	v_mul_f32_e32 v216, v144, v216
	v_mul_f32_e32 v217, v144, v217
	v_mul_f32_e32 v218, v144, v218
	v_mul_f32_e32 v219, v144, v219
	v_mul_f32_e32 v220, v144, v220
	v_mul_f32_e32 v221, v144, v221
	v_mul_f32_e32 v222, v145, v222
	v_mul_f32_e32 v223, v145, v223
	v_mul_f32_e32 v224, v145, v224
	v_mul_f32_e32 v225, v145, v225
	v_mul_f32_e32 v226, v145, v226
	v_mul_f32_e32 v227, v145, v227
	v_mul_f32_e32 v228, v145, v228
	v_mul_f32_e32 v229, v145, v229
	v_mul_f32_e32 v214, v16, v214
	v_mul_f32_e32 v215, v17, v215
	v_mul_f32_e32 v216, v18, v216
	v_mul_f32_e32 v217, v19, v217
	v_mul_f32_e32 v218, v20, v218
	v_mul_f32_e32 v219, v21, v219
	v_mul_f32_e32 v220, v22, v220
	v_mul_f32_e32 v221, v23, v221
	v_mul_f32_e32 v222, v24, v222
	v_mul_f32_e32 v223, v25, v223
	v_mul_f32_e32 v224, v26, v224
	v_mul_f32_e32 v225, v27, v225
	v_mul_f32_e32 v226, v28, v226
	v_mul_f32_e32 v227, v29, v227
	v_mul_f32_e32 v228, v30, v228
	v_mul_f32_e32 v229, v31, v229
	v_mul_f32_e32 v214, v240, v214
	v_mul_f32_e32 v215, v241, v215
	v_mul_f32_e32 v216, v242, v216
	v_mul_f32_e32 v217, v243, v217
	v_mul_f32_e32 v218, v244, v218
	v_mul_f32_e32 v219, v245, v219
	v_mul_f32_e32 v220, v246, v220
	v_mul_f32_e32 v221, v247, v221
	v_mul_f32_e32 v222, v248, v222
	v_mul_f32_e32 v223, v249, v223
	v_mul_f32_e32 v224, v250, v224
	v_mul_f32_e32 v225, v251, v225
	v_mul_f32_e32 v226, v252, v226
	v_mul_f32_e32 v227, v253, v227
	v_mul_f32_e32 v228, v254, v228
	v_mul_f32_e32 v229, v255, v229
	v_cvt_pk_bf16_f32 v144, v214, v215
	v_cvt_pk_bf16_f32 v145, v216, v217
	v_cvt_pk_bf16_f32 v146, v218, v219
	v_cvt_pk_bf16_f32 v147, v220, v221
	v_cvt_pk_bf16_f32 v148, v222, v223
	v_cvt_pk_bf16_f32 v149, v224, v225
	v_cvt_pk_bf16_f32 v150, v226, v227
	v_cvt_pk_bf16_f32 v151, v228, v229
	s_mul_i32 s9, s46, 0
	s_add_i32 s9, s9, s8
	s_lshl_b32 s3, s9, 11
	s_add_u32 s24, s16, s3
	s_addc_u32 s25, s17, 0
	global_store_dwordx4 v2, v[144:147], s[24:25]
	global_store_dwordx4 v2, v[148:151], s[24:25] offset:1024
	s_waitcnt vmcnt(26)
; DI unsigned pk_bf16(float a, float b) { f32x2 v = {a, b}; bf2_t r = __builtin_convertvector(v, bf2_t); return __builtin_bit_cast(unsigned, r); }
; DI float bflo(unsigned u) { return __uint_as_float(u << 16); }
; DI float bfhi(unsigned u) { return __uint_as_float(u & 0xffff0000u); }
; DI float silu_f(float x) { return x * __builtin_amdgcn_rcpf(1.f + __expf(-x)); }
; DI void phase_gdn_gate(const Params& p) {
;     ...
;         const u32x4 z0 = *(const u32x4*)(P0 + (size_t)tok * LDP0 + 3072 + 16 * lane), z1 = *(const u32x4*)(P0 + (size_t)tok * LDP0 + 3072 + 16 * lane + 8);
;         float o[16], z[16];
;         const unsigned au[8] = {a0.x, a0.y, a0.z, a0.w, a1.x, a1.y, a1.z, a1.w}, zu[8] = {z0.x, z0.y, z0.z, z0.w, z1.x, z1.y, z1.z, z1.w};
;         float ss = 0.f;
; #pragma unroll
;         for (int i = 0; i < 8; ++i) { o[2 * i] = bflo(au[i]); o[2 * i + 1] = bfhi(au[i]); z[2 * i] = bflo(zu[i]); z[2 * i + 1] = bfhi(zu[i]); ss += o[2 * i] * o[2 * i] + o[2 * i + 1] * o[2 * i + 1]; }
;         ss += __shfl_xor(ss, 1); ss += __shfl_xor(ss, 2); ss += __shfl_xor(ss, 4);
;         const float rstd = rsqrtf(ss * (1.f / 128.f) + 1e-6f);
;         const int d0 = (16 * lane) & 127;
;         unsigned r[8];
; #pragma unroll
;         for (int i = 0; i < 8; ++i) { const float v0 = o[2 * i] * rstd * p.onorm_a[d0 + 2 * i] * silu_f(z[2 * i]), v1 = o[2 * i + 1] * rstd * p.onorm_a[d0 + 2 * i + 1] * silu_f(z[2 * i + 1]); r[i] = pk_bf16(v0, v1); }
;         *(u32x4*)(og + (size_t)tok * 1024 + 16 * lane) = (u32x4){r[0], r[1], r[2], r[3]};
;         *(u32x4*)(og + (size_t)tok * 1024 + 16 * lane + 8) = (u32x4){r[4], r[5], r[6], r[7]};
	v_lshlrev_b32_e32 v214, 16, v48
	v_and_b32_e32 v215, 0xffff0000, v48
	v_lshlrev_b32_e32 v216, 16, v49
	v_and_b32_e32 v217, 0xffff0000, v49
	v_lshlrev_b32_e32 v218, 16, v50
	v_and_b32_e32 v219, 0xffff0000, v50
	v_lshlrev_b32_e32 v220, 16, v51
	v_and_b32_e32 v221, 0xffff0000, v51
	v_lshlrev_b32_e32 v222, 16, v52
	v_and_b32_e32 v223, 0xffff0000, v52
	v_lshlrev_b32_e32 v224, 16, v53
	v_and_b32_e32 v225, 0xffff0000, v53
	v_lshlrev_b32_e32 v226, 16, v54
	v_and_b32_e32 v227, 0xffff0000, v54
	v_lshlrev_b32_e32 v228, 16, v55
	v_and_b32_e32 v229, 0xffff0000, v55
	v_mul_f32_e32 v144, v214, v214
	v_fmac_f32_e32 v144, v215, v215
	v_fmac_f32_e32 v144, v216, v216
	v_fmac_f32_e32 v144, v217, v217
	v_fmac_f32_e32 v144, v218, v218
	v_fmac_f32_e32 v144, v219, v219
	v_fmac_f32_e32 v144, v220, v220
	v_fmac_f32_e32 v144, v221, v221
	v_mul_f32_e32 v145, v222, v222
	v_fmac_f32_e32 v145, v223, v223
	v_fmac_f32_e32 v145, v224, v224
	v_fmac_f32_e32 v145, v225, v225
	v_fmac_f32_e32 v145, v226, v226
	v_fmac_f32_e32 v145, v227, v227
	v_fmac_f32_e32 v145, v228, v228
	v_fmac_f32_e32 v145, v229, v229
	v_lshlrev_b32_e32 v240, 16, v56
	v_and_b32_e32 v241, 0xffff0000, v56
	v_lshlrev_b32_e32 v242, 16, v57
	v_and_b32_e32 v243, 0xffff0000, v57
	v_lshlrev_b32_e32 v244, 16, v58
	v_and_b32_e32 v245, 0xffff0000, v58
	v_lshlrev_b32_e32 v246, 16, v59
	v_and_b32_e32 v247, 0xffff0000, v59
	v_lshlrev_b32_e32 v248, 16, v60
	v_and_b32_e32 v249, 0xffff0000, v60
	v_lshlrev_b32_e32 v250, 16, v61
	v_and_b32_e32 v251, 0xffff0000, v61
	v_lshlrev_b32_e32 v252, 16, v62
	v_and_b32_e32 v253, 0xffff0000, v62
	v_lshlrev_b32_e32 v254, 16, v63
	v_and_b32_e32 v255, 0xffff0000, v63
	s_nop 1
	v_add_f32_dpp v144, v144, v144 quad_perm:[1,0,3,2] row_mask:0xf bank_mask:0xf
	v_add_f32_dpp v145, v145, v145 quad_perm:[1,0,3,2] row_mask:0xf bank_mask:0xf
	s_nop 1
	v_add_f32_dpp v144, v144, v144 quad_perm:[2,3,0,1] row_mask:0xf bank_mask:0xf
	v_add_f32_dpp v145, v145, v145 quad_perm:[2,3,0,1] row_mask:0xf bank_mask:0xf
	s_nop 1
	v_add_f32_dpp v144, v144, v144 row_ror:4 row_mask:0xf bank_mask:0xf
	v_add_f32_dpp v145, v145, v145 row_ror:4 row_mask:0xf bank_mask:0xf
	s_nop 1
	v_add_f32_dpp v144, v144, v144 row_ror:8 row_mask:0xf bank_mask:0xf
	v_add_f32_dpp v145, v145, v145 row_ror:8 row_mask:0xf bank_mask:0xf
	v_fmamk_f32 v144, v144, 0x3c000000, v15
	v_fmamk_f32 v145, v145, 0x3c000000, v15
	v_rsq_f32_e32 v144, v144
	v_rsq_f32_e32 v145, v145
	v_mul_f32_e32 v148, 0xbfb8aa3b, v240
	v_mul_f32_e32 v149, 0xbfb8aa3b, v241
	v_mul_f32_e32 v150, 0xbfb8aa3b, v242
	v_mul_f32_e32 v151, 0xbfb8aa3b, v243
	v_mul_f32_e32 v4, 0xbfb8aa3b, v244
	v_mul_f32_e32 v5, 0xbfb8aa3b, v245
	v_mul_f32_e32 v6, 0xbfb8aa3b, v246
	v_mul_f32_e32 v7, 0xbfb8aa3b, v247
	v_exp_f32_e32 v148, v148
	v_exp_f32_e32 v149, v149
	v_exp_f32_e32 v150, v150
	v_exp_f32_e32 v151, v151
	v_exp_f32_e32 v4, v4
	v_exp_f32_e32 v5, v5
	v_exp_f32_e32 v6, v6
	v_exp_f32_e32 v7, v7
	v_add_f32_e32 v148, 1.0, v148
	v_add_f32_e32 v149, 1.0, v149
	v_add_f32_e32 v150, 1.0, v150
	v_add_f32_e32 v151, 1.0, v151
	v_add_f32_e32 v4, 1.0, v4
	v_add_f32_e32 v5, 1.0, v5
	v_add_f32_e32 v6, 1.0, v6
	v_add_f32_e32 v7, 1.0, v7
	v_rcp_f32_e32 v148, v148
	v_rcp_f32_e32 v149, v149
	v_rcp_f32_e32 v150, v150
	v_rcp_f32_e32 v151, v151
	v_rcp_f32_e32 v4, v4
	v_rcp_f32_e32 v5, v5
	v_rcp_f32_e32 v6, v6
	v_rcp_f32_e32 v7, v7
	v_mul_f32_e32 v240, v148, v240
	v_mul_f32_e32 v241, v149, v241
	v_mul_f32_e32 v242, v150, v242
	v_mul_f32_e32 v243, v151, v243
	v_mul_f32_e32 v244, v4, v244
	v_mul_f32_e32 v245, v5, v245
	v_mul_f32_e32 v246, v6, v246
	v_mul_f32_e32 v247, v7, v247
	v_mul_f32_e32 v148, 0xbfb8aa3b, v248
	v_mul_f32_e32 v149, 0xbfb8aa3b, v249
	v_mul_f32_e32 v150, 0xbfb8aa3b, v250
	v_mul_f32_e32 v151, 0xbfb8aa3b, v251
	v_mul_f32_e32 v4, 0xbfb8aa3b, v252
	v_mul_f32_e32 v5, 0xbfb8aa3b, v253
	v_mul_f32_e32 v6, 0xbfb8aa3b, v254
	v_mul_f32_e32 v7, 0xbfb8aa3b, v255
	v_exp_f32_e32 v148, v148
	v_exp_f32_e32 v149, v149
	v_exp_f32_e32 v150, v150
	v_exp_f32_e32 v151, v151
	v_exp_f32_e32 v4, v4
	v_exp_f32_e32 v5, v5
	v_exp_f32_e32 v6, v6
	v_exp_f32_e32 v7, v7
	v_add_f32_e32 v148, 1.0, v148
	v_add_f32_e32 v149, 1.0, v149
	v_add_f32_e32 v150, 1.0, v150
	v_add_f32_e32 v151, 1.0, v151
	v_add_f32_e32 v4, 1.0, v4
	v_add_f32_e32 v5, 1.0, v5
	v_add_f32_e32 v6, 1.0, v6
	v_add_f32_e32 v7, 1.0, v7
	v_rcp_f32_e32 v148, v148
	v_rcp_f32_e32 v149, v149
	v_rcp_f32_e32 v150, v150
	v_rcp_f32_e32 v151, v151
	v_rcp_f32_e32 v4, v4
	v_rcp_f32_e32 v5, v5
	v_rcp_f32_e32 v6, v6
	v_rcp_f32_e32 v7, v7
	v_mul_f32_e32 v248, v148, v248
	v_mul_f32_e32 v249, v149, v249
	v_mul_f32_e32 v250, v150, v250
	v_mul_f32_e32 v251, v151, v251
	v_mul_f32_e32 v252, v4, v252
	v_mul_f32_e32 v253, v5, v253
	v_mul_f32_e32 v254, v6, v254
	v_mul_f32_e32 v255, v7, v255
	v_mul_f32_e32 v214, v144, v214
	v_mul_f32_e32 v215, v144, v215
	v_mul_f32_e32 v216, v144, v216
	v_mul_f32_e32 v217, v144, v217
	v_mul_f32_e32 v218, v144, v218
	v_mul_f32_e32 v219, v144, v219
	v_mul_f32_e32 v220, v144, v220
	v_mul_f32_e32 v221, v144, v221
	v_mul_f32_e32 v222, v145, v222
	v_mul_f32_e32 v223, v145, v223
	v_mul_f32_e32 v224, v145, v224
	v_mul_f32_e32 v225, v145, v225
	v_mul_f32_e32 v226, v145, v226
	v_mul_f32_e32 v227, v145, v227
	v_mul_f32_e32 v228, v145, v228
	v_mul_f32_e32 v229, v145, v229
	v_mul_f32_e32 v214, v16, v214
	v_mul_f32_e32 v215, v17, v215
	v_mul_f32_e32 v216, v18, v216
	v_mul_f32_e32 v217, v19, v217
	v_mul_f32_e32 v218, v20, v218
	v_mul_f32_e32 v219, v21, v219
	v_mul_f32_e32 v220, v22, v220
	v_mul_f32_e32 v221, v23, v221
	v_mul_f32_e32 v222, v24, v222
	v_mul_f32_e32 v223, v25, v223
	v_mul_f32_e32 v224, v26, v224
	v_mul_f32_e32 v225, v27, v225
	v_mul_f32_e32 v226, v28, v226
	v_mul_f32_e32 v227, v29, v227
	v_mul_f32_e32 v228, v30, v228
	v_mul_f32_e32 v229, v31, v229
	v_mul_f32_e32 v214, v240, v214
	v_mul_f32_e32 v215, v241, v215
	v_mul_f32_e32 v216, v242, v216
	v_mul_f32_e32 v217, v243, v217
	v_mul_f32_e32 v218, v244, v218
	v_mul_f32_e32 v219, v245, v219
	v_mul_f32_e32 v220, v246, v220
	v_mul_f32_e32 v221, v247, v221
	v_mul_f32_e32 v222, v248, v222
	v_mul_f32_e32 v223, v249, v223
	v_mul_f32_e32 v224, v250, v224
	v_mul_f32_e32 v225, v251, v225
	v_mul_f32_e32 v226, v252, v226
	v_mul_f32_e32 v227, v253, v227
	v_mul_f32_e32 v228, v254, v228
	v_mul_f32_e32 v229, v255, v229
	v_cvt_pk_bf16_f32 v144, v214, v215
	v_cvt_pk_bf16_f32 v145, v216, v217
	v_cvt_pk_bf16_f32 v146, v218, v219
	v_cvt_pk_bf16_f32 v147, v220, v221
	v_cvt_pk_bf16_f32 v148, v222, v223
	v_cvt_pk_bf16_f32 v149, v224, v225
	v_cvt_pk_bf16_f32 v150, v226, v227
	v_cvt_pk_bf16_f32 v151, v228, v229
	s_mul_i32 s9, s46, 1
	s_add_i32 s9, s9, s8
	s_lshl_b32 s3, s9, 11
	s_add_u32 s24, s16, s3
	s_addc_u32 s25, s17, 0
	global_store_dwordx4 v2, v[144:147], s[24:25]
	global_store_dwordx4 v2, v[148:151], s[24:25] offset:1024
	s_waitcnt vmcnt(24)
; DI unsigned pk_bf16(float a, float b) { f32x2 v = {a, b}; bf2_t r = __builtin_convertvector(v, bf2_t); return __builtin_bit_cast(unsigned, r); }
; DI float bflo(unsigned u) { return __uint_as_float(u << 16); }
; DI float bfhi(unsigned u) { return __uint_as_float(u & 0xffff0000u); }
; DI float silu_f(float x) { return x * __builtin_amdgcn_rcpf(1.f + __expf(-x)); }
; DI void phase_gdn_gate(const Params& p) {
;     ...
;         const u32x4 z0 = *(const u32x4*)(P0 + (size_t)tok * LDP0 + 3072 + 16 * lane), z1 = *(const u32x4*)(P0 + (size_t)tok * LDP0 + 3072 + 16 * lane + 8);
;         float o[16], z[16];
;         const unsigned au[8] = {a0.x, a0.y, a0.z, a0.w, a1.x, a1.y, a1.z, a1.w}, zu[8] = {z0.x, z0.y, z0.z, z0.w, z1.x, z1.y, z1.z, z1.w};
;         float ss = 0.f;
; #pragma unroll
;         for (int i = 0; i < 8; ++i) { o[2 * i] = bflo(au[i]); o[2 * i + 1] = bfhi(au[i]); z[2 * i] = bflo(zu[i]); z[2 * i + 1] = bfhi(zu[i]); ss += o[2 * i] * o[2 * i] + o[2 * i + 1] * o[2 * i + 1]; }
;         ss += __shfl_xor(ss, 1); ss += __shfl_xor(ss, 2); ss += __shfl_xor(ss, 4);
;         const float rstd = rsqrtf(ss * (1.f / 128.f) + 1e-6f);
;         const int d0 = (16 * lane) & 127;
;         unsigned r[8];
; #pragma unroll
;         for (int i = 0; i < 8; ++i) { const float v0 = o[2 * i] * rstd * p.onorm_a[d0 + 2 * i] * silu_f(z[2 * i]), v1 = o[2 * i + 1] * rstd * p.onorm_a[d0 + 2 * i + 1] * silu_f(z[2 * i + 1]); r[i] = pk_bf16(v0, v1); }
;         *(u32x4*)(og + (size_t)tok * 1024 + 16 * lane) = (u32x4){r[0], r[1], r[2], r[3]};
;         *(u32x4*)(og + (size_t)tok * 1024 + 16 * lane + 8) = (u32x4){r[4], r[5], r[6], r[7]};
	v_lshlrev_b32_e32 v214, 16, v64
	v_and_b32_e32 v215, 0xffff0000, v64
	v_lshlrev_b32_e32 v216, 16, v65
	v_and_b32_e32 v217, 0xffff0000, v65
	v_lshlrev_b32_e32 v218, 16, v66
	v_and_b32_e32 v219, 0xffff0000, v66
	v_lshlrev_b32_e32 v220, 16, v67
	v_and_b32_e32 v221, 0xffff0000, v67
	v_lshlrev_b32_e32 v222, 16, v68
	v_and_b32_e32 v223, 0xffff0000, v68
	v_lshlrev_b32_e32 v224, 16, v69
	v_and_b32_e32 v225, 0xffff0000, v69
	v_lshlrev_b32_e32 v226, 16, v70
	v_and_b32_e32 v227, 0xffff0000, v70
	v_lshlrev_b32_e32 v228, 16, v71
	v_and_b32_e32 v229, 0xffff0000, v71
	v_mul_f32_e32 v144, v214, v214
	v_fmac_f32_e32 v144, v215, v215
	v_fmac_f32_e32 v144, v216, v216
	v_fmac_f32_e32 v144, v217, v217
	v_fmac_f32_e32 v144, v218, v218
	v_fmac_f32_e32 v144, v219, v219
	v_fmac_f32_e32 v144, v220, v220
	v_fmac_f32_e32 v144, v221, v221
	v_mul_f32_e32 v145, v222, v222
	v_fmac_f32_e32 v145, v223, v223
	v_fmac_f32_e32 v145, v224, v224
	v_fmac_f32_e32 v145, v225, v225
	v_fmac_f32_e32 v145, v226, v226
	v_fmac_f32_e32 v145, v227, v227
	v_fmac_f32_e32 v145, v228, v228
	v_fmac_f32_e32 v145, v229, v229
	v_lshlrev_b32_e32 v240, 16, v72
	v_and_b32_e32 v241, 0xffff0000, v72
	v_lshlrev_b32_e32 v242, 16, v73
	v_and_b32_e32 v243, 0xffff0000, v73
	v_lshlrev_b32_e32 v244, 16, v74
	v_and_b32_e32 v245, 0xffff0000, v74
	v_lshlrev_b32_e32 v246, 16, v75
	v_and_b32_e32 v247, 0xffff0000, v75
	v_lshlrev_b32_e32 v248, 16, v76
	v_and_b32_e32 v249, 0xffff0000, v76
	v_lshlrev_b32_e32 v250, 16, v77
	v_and_b32_e32 v251, 0xffff0000, v77
	v_lshlrev_b32_e32 v252, 16, v78
	v_and_b32_e32 v253, 0xffff0000, v78
	v_lshlrev_b32_e32 v254, 16, v79
	v_and_b32_e32 v255, 0xffff0000, v79
	s_nop 1
	v_add_f32_dpp v144, v144, v144 quad_perm:[1,0,3,2] row_mask:0xf bank_mask:0xf
	v_add_f32_dpp v145, v145, v145 quad_perm:[1,0,3,2] row_mask:0xf bank_mask:0xf
	s_nop 1
	v_add_f32_dpp v144, v144, v144 quad_perm:[2,3,0,1] row_mask:0xf bank_mask:0xf
	v_add_f32_dpp v145, v145, v145 quad_perm:[2,3,0,1] row_mask:0xf bank_mask:0xf
	s_nop 1
	v_add_f32_dpp v144, v144, v144 row_ror:4 row_mask:0xf bank_mask:0xf
	v_add_f32_dpp v145, v145, v145 row_ror:4 row_mask:0xf bank_mask:0xf
	s_nop 1
	v_add_f32_dpp v144, v144, v144 row_ror:8 row_mask:0xf bank_mask:0xf
	v_add_f32_dpp v145, v145, v145 row_ror:8 row_mask:0xf bank_mask:0xf
	v_fmamk_f32 v144, v144, 0x3c000000, v15
	v_fmamk_f32 v145, v145, 0x3c000000, v15
	v_rsq_f32_e32 v144, v144
	v_rsq_f32_e32 v145, v145
	v_mul_f32_e32 v148, 0xbfb8aa3b, v240
	v_mul_f32_e32 v149, 0xbfb8aa3b, v241
	v_mul_f32_e32 v150, 0xbfb8aa3b, v242
	v_mul_f32_e32 v151, 0xbfb8aa3b, v243
	v_mul_f32_e32 v4, 0xbfb8aa3b, v244
	v_mul_f32_e32 v5, 0xbfb8aa3b, v245
	v_mul_f32_e32 v6, 0xbfb8aa3b, v246
	v_mul_f32_e32 v7, 0xbfb8aa3b, v247
	v_exp_f32_e32 v148, v148
	v_exp_f32_e32 v149, v149
	v_exp_f32_e32 v150, v150
	v_exp_f32_e32 v151, v151
	v_exp_f32_e32 v4, v4
	v_exp_f32_e32 v5, v5
	v_exp_f32_e32 v6, v6
	v_exp_f32_e32 v7, v7
	v_add_f32_e32 v148, 1.0, v148
	v_add_f32_e32 v149, 1.0, v149
	v_add_f32_e32 v150, 1.0, v150
	v_add_f32_e32 v151, 1.0, v151
	v_add_f32_e32 v4, 1.0, v4
	v_add_f32_e32 v5, 1.0, v5
	v_add_f32_e32 v6, 1.0, v6
	v_add_f32_e32 v7, 1.0, v7
	v_rcp_f32_e32 v148, v148
	v_rcp_f32_e32 v149, v149
	v_rcp_f32_e32 v150, v150
	v_rcp_f32_e32 v151, v151
	v_rcp_f32_e32 v4, v4
	v_rcp_f32_e32 v5, v5
	v_rcp_f32_e32 v6, v6
	v_rcp_f32_e32 v7, v7
	v_mul_f32_e32 v240, v148, v240
	v_mul_f32_e32 v241, v149, v241
	v_mul_f32_e32 v242, v150, v242
	v_mul_f32_e32 v243, v151, v243
	v_mul_f32_e32 v244, v4, v244
	v_mul_f32_e32 v245, v5, v245
	v_mul_f32_e32 v246, v6, v246
	v_mul_f32_e32 v247, v7, v247
	v_mul_f32_e32 v148, 0xbfb8aa3b, v248
	v_mul_f32_e32 v149, 0xbfb8aa3b, v249
	v_mul_f32_e32 v150, 0xbfb8aa3b, v250
	v_mul_f32_e32 v151, 0xbfb8aa3b, v251
	v_mul_f32_e32 v4, 0xbfb8aa3b, v252
	v_mul_f32_e32 v5, 0xbfb8aa3b, v253
	v_mul_f32_e32 v6, 0xbfb8aa3b, v254
	v_mul_f32_e32 v7, 0xbfb8aa3b, v255
	v_exp_f32_e32 v148, v148
	v_exp_f32_e32 v149, v149
	v_exp_f32_e32 v150, v150
	v_exp_f32_e32 v151, v151
	v_exp_f32_e32 v4, v4
	v_exp_f32_e32 v5, v5
	v_exp_f32_e32 v6, v6
	v_exp_f32_e32 v7, v7
	v_add_f32_e32 v148, 1.0, v148
	v_add_f32_e32 v149, 1.0, v149
	v_add_f32_e32 v150, 1.0, v150
	v_add_f32_e32 v151, 1.0, v151
	v_add_f32_e32 v4, 1.0, v4
	v_add_f32_e32 v5, 1.0, v5
	v_add_f32_e32 v6, 1.0, v6
	v_add_f32_e32 v7, 1.0, v7
	v_rcp_f32_e32 v148, v148
	v_rcp_f32_e32 v149, v149
	v_rcp_f32_e32 v150, v150
	v_rcp_f32_e32 v151, v151
	v_rcp_f32_e32 v4, v4
	v_rcp_f32_e32 v5, v5
	v_rcp_f32_e32 v6, v6
	v_rcp_f32_e32 v7, v7
	v_mul_f32_e32 v248, v148, v248
	v_mul_f32_e32 v249, v149, v249
	v_mul_f32_e32 v250, v150, v250
	v_mul_f32_e32 v251, v151, v251
	v_mul_f32_e32 v252, v4, v252
	v_mul_f32_e32 v253, v5, v253
	v_mul_f32_e32 v254, v6, v254
	v_mul_f32_e32 v255, v7, v255
	v_mul_f32_e32 v214, v144, v214
	v_mul_f32_e32 v215, v144, v215
	v_mul_f32_e32 v216, v144, v216
	v_mul_f32_e32 v217, v144, v217
	v_mul_f32_e32 v218, v144, v218
	v_mul_f32_e32 v219, v144, v219
	v_mul_f32_e32 v220, v144, v220
	v_mul_f32_e32 v221, v144, v221
	v_mul_f32_e32 v222, v145, v222
	v_mul_f32_e32 v223, v145, v223
	v_mul_f32_e32 v224, v145, v224
	v_mul_f32_e32 v225, v145, v225
	v_mul_f32_e32 v226, v145, v226
	v_mul_f32_e32 v227, v145, v227
	v_mul_f32_e32 v228, v145, v228
	v_mul_f32_e32 v229, v145, v229
	v_mul_f32_e32 v214, v16, v214
	v_mul_f32_e32 v215, v17, v215
	v_mul_f32_e32 v216, v18, v216
	v_mul_f32_e32 v217, v19, v217
	v_mul_f32_e32 v218, v20, v218
	v_mul_f32_e32 v219, v21, v219
	v_mul_f32_e32 v220, v22, v220
	v_mul_f32_e32 v221, v23, v221
	v_mul_f32_e32 v222, v24, v222
	v_mul_f32_e32 v223, v25, v223
	v_mul_f32_e32 v224, v26, v224
	v_mul_f32_e32 v225, v27, v225
	v_mul_f32_e32 v226, v28, v226
	v_mul_f32_e32 v227, v29, v227
	v_mul_f32_e32 v228, v30, v228
	v_mul_f32_e32 v229, v31, v229
	v_mul_f32_e32 v214, v240, v214
	v_mul_f32_e32 v215, v241, v215
	v_mul_f32_e32 v216, v242, v216
	v_mul_f32_e32 v217, v243, v217
	v_mul_f32_e32 v218, v244, v218
	v_mul_f32_e32 v219, v245, v219
	v_mul_f32_e32 v220, v246, v220
	v_mul_f32_e32 v221, v247, v221
	v_mul_f32_e32 v222, v248, v222
	v_mul_f32_e32 v223, v249, v223
	v_mul_f32_e32 v224, v250, v224
	v_mul_f32_e32 v225, v251, v225
	v_mul_f32_e32 v226, v252, v226
	v_mul_f32_e32 v227, v253, v227
	v_mul_f32_e32 v228, v254, v228
	v_mul_f32_e32 v229, v255, v229
	v_cvt_pk_bf16_f32 v144, v214, v215
	v_cvt_pk_bf16_f32 v145, v216, v217
	v_cvt_pk_bf16_f32 v146, v218, v219
	v_cvt_pk_bf16_f32 v147, v220, v221
	v_cvt_pk_bf16_f32 v148, v222, v223
	v_cvt_pk_bf16_f32 v149, v224, v225
	v_cvt_pk_bf16_f32 v150, v226, v227
	v_cvt_pk_bf16_f32 v151, v228, v229
	s_mul_i32 s9, s46, 2
	s_add_i32 s9, s9, s8
	s_lshl_b32 s3, s9, 11
	s_add_u32 s24, s16, s3
	s_addc_u32 s25, s17, 0
	global_store_dwordx4 v2, v[144:147], s[24:25]
	global_store_dwordx4 v2, v[148:151], s[24:25] offset:1024
	s_waitcnt vmcnt(22)
; DI unsigned pk_bf16(float a, float b) { f32x2 v = {a, b}; bf2_t r = __builtin_convertvector(v, bf2_t); return __builtin_bit_cast(unsigned, r); }
; DI float bflo(unsigned u) { return __uint_as_float(u << 16); }
; DI float bfhi(unsigned u) { return __uint_as_float(u & 0xffff0000u); }
; DI float silu_f(float x) { return x * __builtin_amdgcn_rcpf(1.f + __expf(-x)); }
; DI void phase_gdn_gate(const Params& p) {
;     ...
;         const u32x4 z0 = *(const u32x4*)(P0 + (size_t)tok * LDP0 + 3072 + 16 * lane), z1 = *(const u32x4*)(P0 + (size_t)tok * LDP0 + 3072 + 16 * lane + 8);
;         float o[16], z[16];
;         const unsigned au[8] = {a0.x, a0.y, a0.z, a0.w, a1.x, a1.y, a1.z, a1.w}, zu[8] = {z0.x, z0.y, z0.z, z0.w, z1.x, z1.y, z1.z, z1.w};
;         float ss = 0.f;
; #pragma unroll
;         for (int i = 0; i < 8; ++i) { o[2 * i] = bflo(au[i]); o[2 * i + 1] = bfhi(au[i]); z[2 * i] = bflo(zu[i]); z[2 * i + 1] = bfhi(zu[i]); ss += o[2 * i] * o[2 * i] + o[2 * i + 1] * o[2 * i + 1]; }
;         ss += __shfl_xor(ss, 1); ss += __shfl_xor(ss, 2); ss += __shfl_xor(ss, 4);
;         const float rstd = rsqrtf(ss * (1.f / 128.f) + 1e-6f);
;         const int d0 = (16 * lane) & 127;
;         unsigned r[8];
; #pragma unroll
;         for (int i = 0; i < 8; ++i) { const float v0 = o[2 * i] * rstd * p.onorm_a[d0 + 2 * i] * silu_f(z[2 * i]), v1 = o[2 * i + 1] * rstd * p.onorm_a[d0 + 2 * i + 1] * silu_f(z[2 * i + 1]); r[i] = pk_bf16(v0, v1); }
;         *(u32x4*)(og + (size_t)tok * 1024 + 16 * lane) = (u32x4){r[0], r[1], r[2], r[3]};
;         *(u32x4*)(og + (size_t)tok * 1024 + 16 * lane + 8) = (u32x4){r[4], r[5], r[6], r[7]};
	v_lshlrev_b32_e32 v214, 16, v80
	v_and_b32_e32 v215, 0xffff0000, v80
	v_lshlrev_b32_e32 v216, 16, v81
	v_and_b32_e32 v217, 0xffff0000, v81
	v_lshlrev_b32_e32 v218, 16, v82
	v_and_b32_e32 v219, 0xffff0000, v82
	v_lshlrev_b32_e32 v220, 16, v83
	v_and_b32_e32 v221, 0xffff0000, v83
	v_lshlrev_b32_e32 v222, 16, v84
	v_and_b32_e32 v223, 0xffff0000, v84
	v_lshlrev_b32_e32 v224, 16, v85
	v_and_b32_e32 v225, 0xffff0000, v85
	v_lshlrev_b32_e32 v226, 16, v86
	v_and_b32_e32 v227, 0xffff0000, v86
	v_lshlrev_b32_e32 v228, 16, v87
	v_and_b32_e32 v229, 0xffff0000, v87
	v_mul_f32_e32 v144, v214, v214
	v_fmac_f32_e32 v144, v215, v215
	v_fmac_f32_e32 v144, v216, v216
	v_fmac_f32_e32 v144, v217, v217
	v_fmac_f32_e32 v144, v218, v218
	v_fmac_f32_e32 v144, v219, v219
	v_fmac_f32_e32 v144, v220, v220
	v_fmac_f32_e32 v144, v221, v221
	v_mul_f32_e32 v145, v222, v222
	v_fmac_f32_e32 v145, v223, v223
	v_fmac_f32_e32 v145, v224, v224
	v_fmac_f32_e32 v145, v225, v225
	v_fmac_f32_e32 v145, v226, v226
	v_fmac_f32_e32 v145, v227, v227
	v_fmac_f32_e32 v145, v228, v228
	v_fmac_f32_e32 v145, v229, v229
	v_lshlrev_b32_e32 v240, 16, v88
	v_and_b32_e32 v241, 0xffff0000, v88
	v_lshlrev_b32_e32 v242, 16, v89
	v_and_b32_e32 v243, 0xffff0000, v89
	v_lshlrev_b32_e32 v244, 16, v90
	v_and_b32_e32 v245, 0xffff0000, v90
	v_lshlrev_b32_e32 v246, 16, v91
	v_and_b32_e32 v247, 0xffff0000, v91
	v_lshlrev_b32_e32 v248, 16, v92
	v_and_b32_e32 v249, 0xffff0000, v92
	v_lshlrev_b32_e32 v250, 16, v93
	v_and_b32_e32 v251, 0xffff0000, v93
	v_lshlrev_b32_e32 v252, 16, v94
	v_and_b32_e32 v253, 0xffff0000, v94
	v_lshlrev_b32_e32 v254, 16, v95
	v_and_b32_e32 v255, 0xffff0000, v95
	s_nop 1
	v_add_f32_dpp v144, v144, v144 quad_perm:[1,0,3,2] row_mask:0xf bank_mask:0xf
	v_add_f32_dpp v145, v145, v145 quad_perm:[1,0,3,2] row_mask:0xf bank_mask:0xf
	s_nop 1
	v_add_f32_dpp v144, v144, v144 quad_perm:[2,3,0,1] row_mask:0xf bank_mask:0xf
	v_add_f32_dpp v145, v145, v145 quad_perm:[2,3,0,1] row_mask:0xf bank_mask:0xf
	s_nop 1
	v_add_f32_dpp v144, v144, v144 row_ror:4 row_mask:0xf bank_mask:0xf
	v_add_f32_dpp v145, v145, v145 row_ror:4 row_mask:0xf bank_mask:0xf
	s_nop 1
	v_add_f32_dpp v144, v144, v144 row_ror:8 row_mask:0xf bank_mask:0xf
	v_add_f32_dpp v145, v145, v145 row_ror:8 row_mask:0xf bank_mask:0xf
	v_fmamk_f32 v144, v144, 0x3c000000, v15
	v_fmamk_f32 v145, v145, 0x3c000000, v15
	v_rsq_f32_e32 v144, v144
	v_rsq_f32_e32 v145, v145
	v_mul_f32_e32 v148, 0xbfb8aa3b, v240
	v_mul_f32_e32 v149, 0xbfb8aa3b, v241
	v_mul_f32_e32 v150, 0xbfb8aa3b, v242
	v_mul_f32_e32 v151, 0xbfb8aa3b, v243
	v_mul_f32_e32 v4, 0xbfb8aa3b, v244
	v_mul_f32_e32 v5, 0xbfb8aa3b, v245
	v_mul_f32_e32 v6, 0xbfb8aa3b, v246
	v_mul_f32_e32 v7, 0xbfb8aa3b, v247
	v_exp_f32_e32 v148, v148
	v_exp_f32_e32 v149, v149
	v_exp_f32_e32 v150, v150
	v_exp_f32_e32 v151, v151
	v_exp_f32_e32 v4, v4
	v_exp_f32_e32 v5, v5
	v_exp_f32_e32 v6, v6
	v_exp_f32_e32 v7, v7
	v_add_f32_e32 v148, 1.0, v148
	v_add_f32_e32 v149, 1.0, v149
	v_add_f32_e32 v150, 1.0, v150
	v_add_f32_e32 v151, 1.0, v151
	v_add_f32_e32 v4, 1.0, v4
	v_add_f32_e32 v5, 1.0, v5
	v_add_f32_e32 v6, 1.0, v6
	v_add_f32_e32 v7, 1.0, v7
	v_rcp_f32_e32 v148, v148
	v_rcp_f32_e32 v149, v149
	v_rcp_f32_e32 v150, v150
	v_rcp_f32_e32 v151, v151
	v_rcp_f32_e32 v4, v4
	v_rcp_f32_e32 v5, v5
	v_rcp_f32_e32 v6, v6
	v_rcp_f32_e32 v7, v7
	v_mul_f32_e32 v240, v148, v240
	v_mul_f32_e32 v241, v149, v241
	v_mul_f32_e32 v242, v150, v242
	v_mul_f32_e32 v243, v151, v243
	v_mul_f32_e32 v244, v4, v244
	v_mul_f32_e32 v245, v5, v245
	v_mul_f32_e32 v246, v6, v246
	v_mul_f32_e32 v247, v7, v247
	v_mul_f32_e32 v148, 0xbfb8aa3b, v248
	v_mul_f32_e32 v149, 0xbfb8aa3b, v249
	v_mul_f32_e32 v150, 0xbfb8aa3b, v250
	v_mul_f32_e32 v151, 0xbfb8aa3b, v251
	v_mul_f32_e32 v4, 0xbfb8aa3b, v252
	v_mul_f32_e32 v5, 0xbfb8aa3b, v253
	v_mul_f32_e32 v6, 0xbfb8aa3b, v254
	v_mul_f32_e32 v7, 0xbfb8aa3b, v255
	v_exp_f32_e32 v148, v148
	v_exp_f32_e32 v149, v149
	v_exp_f32_e32 v150, v150
	v_exp_f32_e32 v151, v151
	v_exp_f32_e32 v4, v4
	v_exp_f32_e32 v5, v5
	v_exp_f32_e32 v6, v6
	v_exp_f32_e32 v7, v7
	v_add_f32_e32 v148, 1.0, v148
	v_add_f32_e32 v149, 1.0, v149
	v_add_f32_e32 v150, 1.0, v150
	v_add_f32_e32 v151, 1.0, v151
	v_add_f32_e32 v4, 1.0, v4
	v_add_f32_e32 v5, 1.0, v5
	v_add_f32_e32 v6, 1.0, v6
	v_add_f32_e32 v7, 1.0, v7
	v_rcp_f32_e32 v148, v148
	v_rcp_f32_e32 v149, v149
	v_rcp_f32_e32 v150, v150
	v_rcp_f32_e32 v151, v151
	v_rcp_f32_e32 v4, v4
	v_rcp_f32_e32 v5, v5
	v_rcp_f32_e32 v6, v6
	v_rcp_f32_e32 v7, v7
	v_mul_f32_e32 v248, v148, v248
	v_mul_f32_e32 v249, v149, v249
	v_mul_f32_e32 v250, v150, v250
	v_mul_f32_e32 v251, v151, v251
	v_mul_f32_e32 v252, v4, v252
	v_mul_f32_e32 v253, v5, v253
	v_mul_f32_e32 v254, v6, v254
	v_mul_f32_e32 v255, v7, v255
	v_mul_f32_e32 v214, v144, v214
	v_mul_f32_e32 v215, v144, v215
	v_mul_f32_e32 v216, v144, v216
	v_mul_f32_e32 v217, v144, v217
	v_mul_f32_e32 v218, v144, v218
	v_mul_f32_e32 v219, v144, v219
	v_mul_f32_e32 v220, v144, v220
	v_mul_f32_e32 v221, v144, v221
	v_mul_f32_e32 v222, v145, v222
	v_mul_f32_e32 v223, v145, v223
	v_mul_f32_e32 v224, v145, v224
	v_mul_f32_e32 v225, v145, v225
	v_mul_f32_e32 v226, v145, v226
	v_mul_f32_e32 v227, v145, v227
	v_mul_f32_e32 v228, v145, v228
	v_mul_f32_e32 v229, v145, v229
	v_mul_f32_e32 v214, v16, v214
	v_mul_f32_e32 v215, v17, v215
	v_mul_f32_e32 v216, v18, v216
	v_mul_f32_e32 v217, v19, v217
	v_mul_f32_e32 v218, v20, v218
	v_mul_f32_e32 v219, v21, v219
	v_mul_f32_e32 v220, v22, v220
	v_mul_f32_e32 v221, v23, v221
	v_mul_f32_e32 v222, v24, v222
	v_mul_f32_e32 v223, v25, v223
	v_mul_f32_e32 v224, v26, v224
	v_mul_f32_e32 v225, v27, v225
	v_mul_f32_e32 v226, v28, v226
	v_mul_f32_e32 v227, v29, v227
	v_mul_f32_e32 v228, v30, v228
	v_mul_f32_e32 v229, v31, v229
	v_mul_f32_e32 v214, v240, v214
	v_mul_f32_e32 v215, v241, v215
	v_mul_f32_e32 v216, v242, v216
	v_mul_f32_e32 v217, v243, v217
	v_mul_f32_e32 v218, v244, v218
	v_mul_f32_e32 v219, v245, v219
	v_mul_f32_e32 v220, v246, v220
	v_mul_f32_e32 v221, v247, v221
	v_mul_f32_e32 v222, v248, v222
	v_mul_f32_e32 v223, v249, v223
	v_mul_f32_e32 v224, v250, v224
	v_mul_f32_e32 v225, v251, v225
	v_mul_f32_e32 v226, v252, v226
	v_mul_f32_e32 v227, v253, v227
	v_mul_f32_e32 v228, v254, v228
	v_mul_f32_e32 v229, v255, v229
	v_cvt_pk_bf16_f32 v144, v214, v215
	v_cvt_pk_bf16_f32 v145, v216, v217
	v_cvt_pk_bf16_f32 v146, v218, v219
	v_cvt_pk_bf16_f32 v147, v220, v221
	v_cvt_pk_bf16_f32 v148, v222, v223
	v_cvt_pk_bf16_f32 v149, v224, v225
	v_cvt_pk_bf16_f32 v150, v226, v227
	v_cvt_pk_bf16_f32 v151, v228, v229
	s_mul_i32 s9, s46, 3
	s_add_i32 s9, s9, s8
	s_lshl_b32 s3, s9, 11
	s_add_u32 s24, s16, s3
	s_addc_u32 s25, s17, 0
	global_store_dwordx4 v2, v[144:147], s[24:25]
	global_store_dwordx4 v2, v[148:151], s[24:25] offset:1024
	s_waitcnt vmcnt(20)
; DI unsigned pk_bf16(float a, float b) { f32x2 v = {a, b}; bf2_t r = __builtin_convertvector(v, bf2_t); return __builtin_bit_cast(unsigned, r); }
; DI float bflo(unsigned u) { return __uint_as_float(u << 16); }
; DI float bfhi(unsigned u) { return __uint_as_float(u & 0xffff0000u); }
; DI float silu_f(float x) { return x * __builtin_amdgcn_rcpf(1.f + __expf(-x)); }
; DI void phase_gdn_gate(const Params& p) {
;     ...
;         const u32x4 z0 = *(const u32x4*)(P0 + (size_t)tok * LDP0 + 3072 + 16 * lane), z1 = *(const u32x4*)(P0 + (size_t)tok * LDP0 + 3072 + 16 * lane + 8);
;         float o[16], z[16];
;         const unsigned au[8] = {a0.x, a0.y, a0.z, a0.w, a1.x, a1.y, a1.z, a1.w}, zu[8] = {z0.x, z0.y, z0.z, z0.w, z1.x, z1.y, z1.z, z1.w};
;         float ss = 0.f;
; #pragma unroll
;         for (int i = 0; i < 8; ++i) { o[2 * i] = bflo(au[i]); o[2 * i + 1] = bfhi(au[i]); z[2 * i] = bflo(zu[i]); z[2 * i + 1] = bfhi(zu[i]); ss += o[2 * i] * o[2 * i] + o[2 * i + 1] * o[2 * i + 1]; }
;         ss += __shfl_xor(ss, 1); ss += __shfl_xor(ss, 2); ss += __shfl_xor(ss, 4);
;         const float rstd = rsqrtf(ss * (1.f / 128.f) + 1e-6f);
;         const int d0 = (16 * lane) & 127;
;         unsigned r[8];
; #pragma unroll
;         for (int i = 0; i < 8; ++i) { const float v0 = o[2 * i] * rstd * p.onorm_a[d0 + 2 * i] * silu_f(z[2 * i]), v1 = o[2 * i + 1] * rstd * p.onorm_a[d0 + 2 * i + 1] * silu_f(z[2 * i + 1]); r[i] = pk_bf16(v0, v1); }
;         *(u32x4*)(og + (size_t)tok * 1024 + 16 * lane) = (u32x4){r[0], r[1], r[2], r[3]};
;         *(u32x4*)(og + (size_t)tok * 1024 + 16 * lane + 8) = (u32x4){r[4], r[5], r[6], r[7]};
	v_lshlrev_b32_e32 v214, 16, v96
	v_and_b32_e32 v215, 0xffff0000, v96
	v_lshlrev_b32_e32 v216, 16, v97
	v_and_b32_e32 v217, 0xffff0000, v97
	v_lshlrev_b32_e32 v218, 16, v98
	v_and_b32_e32 v219, 0xffff0000, v98
	v_lshlrev_b32_e32 v220, 16, v99
	v_and_b32_e32 v221, 0xffff0000, v99
	v_lshlrev_b32_e32 v222, 16, v100
	v_and_b32_e32 v223, 0xffff0000, v100
	v_lshlrev_b32_e32 v224, 16, v101
	v_and_b32_e32 v225, 0xffff0000, v101
	v_lshlrev_b32_e32 v226, 16, v102
	v_and_b32_e32 v227, 0xffff0000, v102
	v_lshlrev_b32_e32 v228, 16, v103
	v_and_b32_e32 v229, 0xffff0000, v103
	v_mul_f32_e32 v144, v214, v214
	v_fmac_f32_e32 v144, v215, v215
	v_fmac_f32_e32 v144, v216, v216
	v_fmac_f32_e32 v144, v217, v217
	v_fmac_f32_e32 v144, v218, v218
	v_fmac_f32_e32 v144, v219, v219
	v_fmac_f32_e32 v144, v220, v220
	v_fmac_f32_e32 v144, v221, v221
	v_mul_f32_e32 v145, v222, v222
	v_fmac_f32_e32 v145, v223, v223
	v_fmac_f32_e32 v145, v224, v224
	v_fmac_f32_e32 v145, v225, v225
	v_fmac_f32_e32 v145, v226, v226
	v_fmac_f32_e32 v145, v227, v227
	v_fmac_f32_e32 v145, v228, v228
	v_fmac_f32_e32 v145, v229, v229
	v_lshlrev_b32_e32 v240, 16, v104
	v_and_b32_e32 v241, 0xffff0000, v104
	v_lshlrev_b32_e32 v242, 16, v105
	v_and_b32_e32 v243, 0xffff0000, v105
	v_lshlrev_b32_e32 v244, 16, v106
	v_and_b32_e32 v245, 0xffff0000, v106
	v_lshlrev_b32_e32 v246, 16, v107
	v_and_b32_e32 v247, 0xffff0000, v107
	v_lshlrev_b32_e32 v248, 16, v108
	v_and_b32_e32 v249, 0xffff0000, v108
	v_lshlrev_b32_e32 v250, 16, v109
	v_and_b32_e32 v251, 0xffff0000, v109
	v_lshlrev_b32_e32 v252, 16, v110
	v_and_b32_e32 v253, 0xffff0000, v110
	v_lshlrev_b32_e32 v254, 16, v111
	v_and_b32_e32 v255, 0xffff0000, v111
	s_nop 1
	v_add_f32_dpp v144, v144, v144 quad_perm:[1,0,3,2] row_mask:0xf bank_mask:0xf
	v_add_f32_dpp v145, v145, v145 quad_perm:[1,0,3,2] row_mask:0xf bank_mask:0xf
	s_nop 1
	v_add_f32_dpp v144, v144, v144 quad_perm:[2,3,0,1] row_mask:0xf bank_mask:0xf
	v_add_f32_dpp v145, v145, v145 quad_perm:[2,3,0,1] row_mask:0xf bank_mask:0xf
	s_nop 1
	v_add_f32_dpp v144, v144, v144 row_ror:4 row_mask:0xf bank_mask:0xf
	v_add_f32_dpp v145, v145, v145 row_ror:4 row_mask:0xf bank_mask:0xf
	s_nop 1
	v_add_f32_dpp v144, v144, v144 row_ror:8 row_mask:0xf bank_mask:0xf
	v_add_f32_dpp v145, v145, v145 row_ror:8 row_mask:0xf bank_mask:0xf
	v_fmamk_f32 v144, v144, 0x3c000000, v15
	v_fmamk_f32 v145, v145, 0x3c000000, v15
	v_rsq_f32_e32 v144, v144
	v_rsq_f32_e32 v145, v145
	v_mul_f32_e32 v148, 0xbfb8aa3b, v240
	v_mul_f32_e32 v149, 0xbfb8aa3b, v241
	v_mul_f32_e32 v150, 0xbfb8aa3b, v242
	v_mul_f32_e32 v151, 0xbfb8aa3b, v243
	v_mul_f32_e32 v4, 0xbfb8aa3b, v244
	v_mul_f32_e32 v5, 0xbfb8aa3b, v245
	v_mul_f32_e32 v6, 0xbfb8aa3b, v246
	v_mul_f32_e32 v7, 0xbfb8aa3b, v247
	v_exp_f32_e32 v148, v148
	v_exp_f32_e32 v149, v149
	v_exp_f32_e32 v150, v150
	v_exp_f32_e32 v151, v151
	v_exp_f32_e32 v4, v4
	v_exp_f32_e32 v5, v5
	v_exp_f32_e32 v6, v6
	v_exp_f32_e32 v7, v7
	v_add_f32_e32 v148, 1.0, v148
	v_add_f32_e32 v149, 1.0, v149
	v_add_f32_e32 v150, 1.0, v150
	v_add_f32_e32 v151, 1.0, v151
	v_add_f32_e32 v4, 1.0, v4
	v_add_f32_e32 v5, 1.0, v5
	v_add_f32_e32 v6, 1.0, v6
	v_add_f32_e32 v7, 1.0, v7
	v_rcp_f32_e32 v148, v148
	v_rcp_f32_e32 v149, v149
	v_rcp_f32_e32 v150, v150
	v_rcp_f32_e32 v151, v151
	v_rcp_f32_e32 v4, v4
	v_rcp_f32_e32 v5, v5
	v_rcp_f32_e32 v6, v6
	v_rcp_f32_e32 v7, v7
	v_mul_f32_e32 v240, v148, v240
	v_mul_f32_e32 v241, v149, v241
	v_mul_f32_e32 v242, v150, v242
	v_mul_f32_e32 v243, v151, v243
	v_mul_f32_e32 v244, v4, v244
	v_mul_f32_e32 v245, v5, v245
	v_mul_f32_e32 v246, v6, v246
	v_mul_f32_e32 v247, v7, v247
	v_mul_f32_e32 v148, 0xbfb8aa3b, v248
	v_mul_f32_e32 v149, 0xbfb8aa3b, v249
	v_mul_f32_e32 v150, 0xbfb8aa3b, v250
	v_mul_f32_e32 v151, 0xbfb8aa3b, v251
	v_mul_f32_e32 v4, 0xbfb8aa3b, v252
	v_mul_f32_e32 v5, 0xbfb8aa3b, v253
	v_mul_f32_e32 v6, 0xbfb8aa3b, v254
	v_mul_f32_e32 v7, 0xbfb8aa3b, v255
	v_exp_f32_e32 v148, v148
	v_exp_f32_e32 v149, v149
	v_exp_f32_e32 v150, v150
	v_exp_f32_e32 v151, v151
	v_exp_f32_e32 v4, v4
	v_exp_f32_e32 v5, v5
	v_exp_f32_e32 v6, v6
	v_exp_f32_e32 v7, v7
	v_add_f32_e32 v148, 1.0, v148
	v_add_f32_e32 v149, 1.0, v149
	v_add_f32_e32 v150, 1.0, v150
	v_add_f32_e32 v151, 1.0, v151
	v_add_f32_e32 v4, 1.0, v4
	v_add_f32_e32 v5, 1.0, v5
	v_add_f32_e32 v6, 1.0, v6
	v_add_f32_e32 v7, 1.0, v7
	v_rcp_f32_e32 v148, v148
	v_rcp_f32_e32 v149, v149
	v_rcp_f32_e32 v150, v150
	v_rcp_f32_e32 v151, v151
	v_rcp_f32_e32 v4, v4
	v_rcp_f32_e32 v5, v5
	v_rcp_f32_e32 v6, v6
	v_rcp_f32_e32 v7, v7
	v_mul_f32_e32 v248, v148, v248
	v_mul_f32_e32 v249, v149, v249
	v_mul_f32_e32 v250, v150, v250
	v_mul_f32_e32 v251, v151, v251
	v_mul_f32_e32 v252, v4, v252
	v_mul_f32_e32 v253, v5, v253
	v_mul_f32_e32 v254, v6, v254
	v_mul_f32_e32 v255, v7, v255
	v_mul_f32_e32 v214, v144, v214
	v_mul_f32_e32 v215, v144, v215
	v_mul_f32_e32 v216, v144, v216
	v_mul_f32_e32 v217, v144, v217
	v_mul_f32_e32 v218, v144, v218
	v_mul_f32_e32 v219, v144, v219
	v_mul_f32_e32 v220, v144, v220
	v_mul_f32_e32 v221, v144, v221
	v_mul_f32_e32 v222, v145, v222
	v_mul_f32_e32 v223, v145, v223
	v_mul_f32_e32 v224, v145, v224
	v_mul_f32_e32 v225, v145, v225
	v_mul_f32_e32 v226, v145, v226
	v_mul_f32_e32 v227, v145, v227
	v_mul_f32_e32 v228, v145, v228
	v_mul_f32_e32 v229, v145, v229
	v_mul_f32_e32 v214, v16, v214
	v_mul_f32_e32 v215, v17, v215
	v_mul_f32_e32 v216, v18, v216
	v_mul_f32_e32 v217, v19, v217
	v_mul_f32_e32 v218, v20, v218
	v_mul_f32_e32 v219, v21, v219
	v_mul_f32_e32 v220, v22, v220
	v_mul_f32_e32 v221, v23, v221
	v_mul_f32_e32 v222, v24, v222
	v_mul_f32_e32 v223, v25, v223
	v_mul_f32_e32 v224, v26, v224
	v_mul_f32_e32 v225, v27, v225
	v_mul_f32_e32 v226, v28, v226
	v_mul_f32_e32 v227, v29, v227
	v_mul_f32_e32 v228, v30, v228
	v_mul_f32_e32 v229, v31, v229
	v_mul_f32_e32 v214, v240, v214
	v_mul_f32_e32 v215, v241, v215
	v_mul_f32_e32 v216, v242, v216
	v_mul_f32_e32 v217, v243, v217
	v_mul_f32_e32 v218, v244, v218
	v_mul_f32_e32 v219, v245, v219
	v_mul_f32_e32 v220, v246, v220
	v_mul_f32_e32 v221, v247, v221
	v_mul_f32_e32 v222, v248, v222
	v_mul_f32_e32 v223, v249, v223
	v_mul_f32_e32 v224, v250, v224
	v_mul_f32_e32 v225, v251, v225
	v_mul_f32_e32 v226, v252, v226
	v_mul_f32_e32 v227, v253, v227
	v_mul_f32_e32 v228, v254, v228
	v_mul_f32_e32 v229, v255, v229
	v_cvt_pk_bf16_f32 v144, v214, v215
	v_cvt_pk_bf16_f32 v145, v216, v217
	v_cvt_pk_bf16_f32 v146, v218, v219
	v_cvt_pk_bf16_f32 v147, v220, v221
	v_cvt_pk_bf16_f32 v148, v222, v223
	v_cvt_pk_bf16_f32 v149, v224, v225
	v_cvt_pk_bf16_f32 v150, v226, v227
	v_cvt_pk_bf16_f32 v151, v228, v229
	s_mul_i32 s9, s46, 4
	s_add_i32 s9, s9, s8
	s_lshl_b32 s3, s9, 11
	s_add_u32 s24, s16, s3
	s_addc_u32 s25, s17, 0
	global_store_dwordx4 v2, v[144:147], s[24:25]
	global_store_dwordx4 v2, v[148:151], s[24:25] offset:1024
	s_waitcnt vmcnt(18)
; DI unsigned pk_bf16(float a, float b) { f32x2 v = {a, b}; bf2_t r = __builtin_convertvector(v, bf2_t); return __builtin_bit_cast(unsigned, r); }
; DI float bflo(unsigned u) { return __uint_as_float(u << 16); }
; DI float bfhi(unsigned u) { return __uint_as_float(u & 0xffff0000u); }
; DI float silu_f(float x) { return x * __builtin_amdgcn_rcpf(1.f + __expf(-x)); }
; DI void phase_gdn_gate(const Params& p) {
;     ...
;         const u32x4 z0 = *(const u32x4*)(P0 + (size_t)tok * LDP0 + 3072 + 16 * lane), z1 = *(const u32x4*)(P0 + (size_t)tok * LDP0 + 3072 + 16 * lane + 8);
;         float o[16], z[16];
;         const unsigned au[8] = {a0.x, a0.y, a0.z, a0.w, a1.x, a1.y, a1.z, a1.w}, zu[8] = {z0.x, z0.y, z0.z, z0.w, z1.x, z1.y, z1.z, z1.w};
;         float ss = 0.f;
; #pragma unroll
;         for (int i = 0; i < 8; ++i) { o[2 * i] = bflo(au[i]); o[2 * i + 1] = bfhi(au[i]); z[2 * i] = bflo(zu[i]); z[2 * i + 1] = bfhi(zu[i]); ss += o[2 * i] * o[2 * i] + o[2 * i + 1] * o[2 * i + 1]; }
;         ss += __shfl_xor(ss, 1); ss += __shfl_xor(ss, 2); ss += __shfl_xor(ss, 4);
;         const float rstd = rsqrtf(ss * (1.f / 128.f) + 1e-6f);
;         const int d0 = (16 * lane) & 127;
;         unsigned r[8];
; #pragma unroll
;         for (int i = 0; i < 8; ++i) { const float v0 = o[2 * i] * rstd * p.onorm_a[d0 + 2 * i] * silu_f(z[2 * i]), v1 = o[2 * i + 1] * rstd * p.onorm_a[d0 + 2 * i + 1] * silu_f(z[2 * i + 1]); r[i] = pk_bf16(v0, v1); }
;         *(u32x4*)(og + (size_t)tok * 1024 + 16 * lane) = (u32x4){r[0], r[1], r[2], r[3]};
;         *(u32x4*)(og + (size_t)tok * 1024 + 16 * lane + 8) = (u32x4){r[4], r[5], r[6], r[7]};
	v_lshlrev_b32_e32 v214, 16, v112
	v_and_b32_e32 v215, 0xffff0000, v112
	v_lshlrev_b32_e32 v216, 16, v113
	v_and_b32_e32 v217, 0xffff0000, v113
	v_lshlrev_b32_e32 v218, 16, v114
	v_and_b32_e32 v219, 0xffff0000, v114
	v_lshlrev_b32_e32 v220, 16, v115
	v_and_b32_e32 v221, 0xffff0000, v115
	v_lshlrev_b32_e32 v222, 16, v116
	v_and_b32_e32 v223, 0xffff0000, v116
	v_lshlrev_b32_e32 v224, 16, v117
	v_and_b32_e32 v225, 0xffff0000, v117
	v_lshlrev_b32_e32 v226, 16, v118
	v_and_b32_e32 v227, 0xffff0000, v118
	v_lshlrev_b32_e32 v228, 16, v119
	v_and_b32_e32 v229, 0xffff0000, v119
	v_mul_f32_e32 v144, v214, v214
	v_fmac_f32_e32 v144, v215, v215
	v_fmac_f32_e32 v144, v216, v216
	v_fmac_f32_e32 v144, v217, v217
	v_fmac_f32_e32 v144, v218, v218
	v_fmac_f32_e32 v144, v219, v219
	v_fmac_f32_e32 v144, v220, v220
	v_fmac_f32_e32 v144, v221, v221
	v_mul_f32_e32 v145, v222, v222
	v_fmac_f32_e32 v145, v223, v223
	v_fmac_f32_e32 v145, v224, v224
	v_fmac_f32_e32 v145, v225, v225
	v_fmac_f32_e32 v145, v226, v226
	v_fmac_f32_e32 v145, v227, v227
	v_fmac_f32_e32 v145, v228, v228
	v_fmac_f32_e32 v145, v229, v229
	v_lshlrev_b32_e32 v240, 16, v120
	v_and_b32_e32 v241, 0xffff0000, v120
	v_lshlrev_b32_e32 v242, 16, v121
	v_and_b32_e32 v243, 0xffff0000, v121
	v_lshlrev_b32_e32 v244, 16, v122
	v_and_b32_e32 v245, 0xffff0000, v122
	v_lshlrev_b32_e32 v246, 16, v123
	v_and_b32_e32 v247, 0xffff0000, v123
	v_lshlrev_b32_e32 v248, 16, v124
	v_and_b32_e32 v249, 0xffff0000, v124
	v_lshlrev_b32_e32 v250, 16, v125
	v_and_b32_e32 v251, 0xffff0000, v125
	v_lshlrev_b32_e32 v252, 16, v126
	v_and_b32_e32 v253, 0xffff0000, v126
	v_lshlrev_b32_e32 v254, 16, v127
	v_and_b32_e32 v255, 0xffff0000, v127
	s_nop 1
	v_add_f32_dpp v144, v144, v144 quad_perm:[1,0,3,2] row_mask:0xf bank_mask:0xf
	v_add_f32_dpp v145, v145, v145 quad_perm:[1,0,3,2] row_mask:0xf bank_mask:0xf
	s_nop 1
	v_add_f32_dpp v144, v144, v144 quad_perm:[2,3,0,1] row_mask:0xf bank_mask:0xf
	v_add_f32_dpp v145, v145, v145 quad_perm:[2,3,0,1] row_mask:0xf bank_mask:0xf
	s_nop 1
	v_add_f32_dpp v144, v144, v144 row_ror:4 row_mask:0xf bank_mask:0xf
	v_add_f32_dpp v145, v145, v145 row_ror:4 row_mask:0xf bank_mask:0xf
	s_nop 1
	v_add_f32_dpp v144, v144, v144 row_ror:8 row_mask:0xf bank_mask:0xf
	v_add_f32_dpp v145, v145, v145 row_ror:8 row_mask:0xf bank_mask:0xf
	v_fmamk_f32 v144, v144, 0x3c000000, v15
	v_fmamk_f32 v145, v145, 0x3c000000, v15
	v_rsq_f32_e32 v144, v144
	v_rsq_f32_e32 v145, v145
	v_mul_f32_e32 v148, 0xbfb8aa3b, v240
	v_mul_f32_e32 v149, 0xbfb8aa3b, v241
	v_mul_f32_e32 v150, 0xbfb8aa3b, v242
	v_mul_f32_e32 v151, 0xbfb8aa3b, v243
	v_mul_f32_e32 v4, 0xbfb8aa3b, v244
	v_mul_f32_e32 v5, 0xbfb8aa3b, v245
	v_mul_f32_e32 v6, 0xbfb8aa3b, v246
	v_mul_f32_e32 v7, 0xbfb8aa3b, v247
	v_exp_f32_e32 v148, v148
	v_exp_f32_e32 v149, v149
	v_exp_f32_e32 v150, v150
	v_exp_f32_e32 v151, v151
	v_exp_f32_e32 v4, v4
	v_exp_f32_e32 v5, v5
	v_exp_f32_e32 v6, v6
	v_exp_f32_e32 v7, v7
	v_add_f32_e32 v148, 1.0, v148
	v_add_f32_e32 v149, 1.0, v149
	v_add_f32_e32 v150, 1.0, v150
	v_add_f32_e32 v151, 1.0, v151
	v_add_f32_e32 v4, 1.0, v4
	v_add_f32_e32 v5, 1.0, v5
	v_add_f32_e32 v6, 1.0, v6
	v_add_f32_e32 v7, 1.0, v7
	v_rcp_f32_e32 v148, v148
	v_rcp_f32_e32 v149, v149
	v_rcp_f32_e32 v150, v150
	v_rcp_f32_e32 v151, v151
	v_rcp_f32_e32 v4, v4
	v_rcp_f32_e32 v5, v5
	v_rcp_f32_e32 v6, v6
	v_rcp_f32_e32 v7, v7
	v_mul_f32_e32 v240, v148, v240
	v_mul_f32_e32 v241, v149, v241
	v_mul_f32_e32 v242, v150, v242
	v_mul_f32_e32 v243, v151, v243
	v_mul_f32_e32 v244, v4, v244
	v_mul_f32_e32 v245, v5, v245
	v_mul_f32_e32 v246, v6, v246
	v_mul_f32_e32 v247, v7, v247
	v_mul_f32_e32 v148, 0xbfb8aa3b, v248
	v_mul_f32_e32 v149, 0xbfb8aa3b, v249
	v_mul_f32_e32 v150, 0xbfb8aa3b, v250
	v_mul_f32_e32 v151, 0xbfb8aa3b, v251
	v_mul_f32_e32 v4, 0xbfb8aa3b, v252
	v_mul_f32_e32 v5, 0xbfb8aa3b, v253
	v_mul_f32_e32 v6, 0xbfb8aa3b, v254
	v_mul_f32_e32 v7, 0xbfb8aa3b, v255
	v_exp_f32_e32 v148, v148
	v_exp_f32_e32 v149, v149
	v_exp_f32_e32 v150, v150
	v_exp_f32_e32 v151, v151
	v_exp_f32_e32 v4, v4
	v_exp_f32_e32 v5, v5
	v_exp_f32_e32 v6, v6
	v_exp_f32_e32 v7, v7
	v_add_f32_e32 v148, 1.0, v148
	v_add_f32_e32 v149, 1.0, v149
	v_add_f32_e32 v150, 1.0, v150
	v_add_f32_e32 v151, 1.0, v151
	v_add_f32_e32 v4, 1.0, v4
	v_add_f32_e32 v5, 1.0, v5
	v_add_f32_e32 v6, 1.0, v6
	v_add_f32_e32 v7, 1.0, v7
	v_rcp_f32_e32 v148, v148
	v_rcp_f32_e32 v149, v149
	v_rcp_f32_e32 v150, v150
	v_rcp_f32_e32 v151, v151
	v_rcp_f32_e32 v4, v4
	v_rcp_f32_e32 v5, v5
	v_rcp_f32_e32 v6, v6
	v_rcp_f32_e32 v7, v7
	v_mul_f32_e32 v248, v148, v248
	v_mul_f32_e32 v249, v149, v249
	v_mul_f32_e32 v250, v150, v250
	v_mul_f32_e32 v251, v151, v251
	v_mul_f32_e32 v252, v4, v252
	v_mul_f32_e32 v253, v5, v253
	v_mul_f32_e32 v254, v6, v254
	v_mul_f32_e32 v255, v7, v255
	v_mul_f32_e32 v214, v144, v214
	v_mul_f32_e32 v215, v144, v215
	v_mul_f32_e32 v216, v144, v216
	v_mul_f32_e32 v217, v144, v217
	v_mul_f32_e32 v218, v144, v218
	v_mul_f32_e32 v219, v144, v219
	v_mul_f32_e32 v220, v144, v220
	v_mul_f32_e32 v221, v144, v221
	v_mul_f32_e32 v222, v145, v222
	v_mul_f32_e32 v223, v145, v223
	v_mul_f32_e32 v224, v145, v224
	v_mul_f32_e32 v225, v145, v225
	v_mul_f32_e32 v226, v145, v226
	v_mul_f32_e32 v227, v145, v227
	v_mul_f32_e32 v228, v145, v228
	v_mul_f32_e32 v229, v145, v229
	v_mul_f32_e32 v214, v16, v214
	v_mul_f32_e32 v215, v17, v215
	v_mul_f32_e32 v216, v18, v216
	v_mul_f32_e32 v217, v19, v217
	v_mul_f32_e32 v218, v20, v218
	v_mul_f32_e32 v219, v21, v219
	v_mul_f32_e32 v220, v22, v220
	v_mul_f32_e32 v221, v23, v221
	v_mul_f32_e32 v222, v24, v222
	v_mul_f32_e32 v223, v25, v223
	v_mul_f32_e32 v224, v26, v224
	v_mul_f32_e32 v225, v27, v225
	v_mul_f32_e32 v226, v28, v226
	v_mul_f32_e32 v227, v29, v227
	v_mul_f32_e32 v228, v30, v228
	v_mul_f32_e32 v229, v31, v229
	v_mul_f32_e32 v214, v240, v214
	v_mul_f32_e32 v215, v241, v215
	v_mul_f32_e32 v216, v242, v216
	v_mul_f32_e32 v217, v243, v217
	v_mul_f32_e32 v218, v244, v218
	v_mul_f32_e32 v219, v245, v219
	v_mul_f32_e32 v220, v246, v220
	v_mul_f32_e32 v221, v247, v221
	v_mul_f32_e32 v222, v248, v222
	v_mul_f32_e32 v223, v249, v223
	v_mul_f32_e32 v224, v250, v224
	v_mul_f32_e32 v225, v251, v225
	v_mul_f32_e32 v226, v252, v226
	v_mul_f32_e32 v227, v253, v227
	v_mul_f32_e32 v228, v254, v228
	v_mul_f32_e32 v229, v255, v229
	v_cvt_pk_bf16_f32 v144, v214, v215
	v_cvt_pk_bf16_f32 v145, v216, v217
	v_cvt_pk_bf16_f32 v146, v218, v219
	v_cvt_pk_bf16_f32 v147, v220, v221
	v_cvt_pk_bf16_f32 v148, v222, v223
	v_cvt_pk_bf16_f32 v149, v224, v225
	v_cvt_pk_bf16_f32 v150, v226, v227
	v_cvt_pk_bf16_f32 v151, v228, v229
	s_mul_i32 s9, s46, 5
	s_add_i32 s9, s9, s8
	s_lshl_b32 s3, s9, 11
	s_add_u32 s24, s16, s3
	s_addc_u32 s25, s17, 0
	global_store_dwordx4 v2, v[144:147], s[24:25]
	global_store_dwordx4 v2, v[148:151], s[24:25] offset:1024
	s_waitcnt vmcnt(16)
; DI unsigned pk_bf16(float a, float b) { f32x2 v = {a, b}; bf2_t r = __builtin_convertvector(v, bf2_t); return __builtin_bit_cast(unsigned, r); }
; DI float bflo(unsigned u) { return __uint_as_float(u << 16); }
; DI float bfhi(unsigned u) { return __uint_as_float(u & 0xffff0000u); }
; DI float silu_f(float x) { return x * __builtin_amdgcn_rcpf(1.f + __expf(-x)); }
; DI void phase_gdn_gate(const Params& p) {
;     ...
;         const u32x4 z0 = *(const u32x4*)(P0 + (size_t)tok * LDP0 + 3072 + 16 * lane), z1 = *(const u32x4*)(P0 + (size_t)tok * LDP0 + 3072 + 16 * lane + 8);
;         float o[16], z[16];
;         const unsigned au[8] = {a0.x, a0.y, a0.z, a0.w, a1.x, a1.y, a1.z, a1.w}, zu[8] = {z0.x, z0.y, z0.z, z0.w, z1.x, z1.y, z1.z, z1.w};
;         float ss = 0.f;
; #pragma unroll
;         for (int i = 0; i < 8; ++i) { o[2 * i] = bflo(au[i]); o[2 * i + 1] = bfhi(au[i]); z[2 * i] = bflo(zu[i]); z[2 * i + 1] = bfhi(zu[i]); ss += o[2 * i] * o[2 * i] + o[2 * i + 1] * o[2 * i + 1]; }
;         ss += __shfl_xor(ss, 1); ss += __shfl_xor(ss, 2); ss += __shfl_xor(ss, 4);
;         const float rstd = rsqrtf(ss * (1.f / 128.f) + 1e-6f);
;         const int d0 = (16 * lane) & 127;
;         unsigned r[8];
; #pragma unroll
;         for (int i = 0; i < 8; ++i) { const float v0 = o[2 * i] * rstd * p.onorm_a[d0 + 2 * i] * silu_f(z[2 * i]), v1 = o[2 * i + 1] * rstd * p.onorm_a[d0 + 2 * i + 1] * silu_f(z[2 * i + 1]); r[i] = pk_bf16(v0, v1); }
;         *(u32x4*)(og + (size_t)tok * 1024 + 16 * lane) = (u32x4){r[0], r[1], r[2], r[3]};
;         *(u32x4*)(og + (size_t)tok * 1024 + 16 * lane + 8) = (u32x4){r[4], r[5], r[6], r[7]};
	v_lshlrev_b32_e32 v214, 16, v128
	v_and_b32_e32 v215, 0xffff0000, v128
	v_lshlrev_b32_e32 v216, 16, v129
	v_and_b32_e32 v217, 0xffff0000, v129
	v_lshlrev_b32_e32 v218, 16, v130
	v_and_b32_e32 v219, 0xffff0000, v130
	v_lshlrev_b32_e32 v220, 16, v131
	v_and_b32_e32 v221, 0xffff0000, v131
	v_lshlrev_b32_e32 v222, 16, v132
	v_and_b32_e32 v223, 0xffff0000, v132
	v_lshlrev_b32_e32 v224, 16, v133
	v_and_b32_e32 v225, 0xffff0000, v133
	v_lshlrev_b32_e32 v226, 16, v134
	v_and_b32_e32 v227, 0xffff0000, v134
	v_lshlrev_b32_e32 v228, 16, v135
	v_and_b32_e32 v229, 0xffff0000, v135
	v_mul_f32_e32 v144, v214, v214
	v_fmac_f32_e32 v144, v215, v215
	v_fmac_f32_e32 v144, v216, v216
	v_fmac_f32_e32 v144, v217, v217
	v_fmac_f32_e32 v144, v218, v218
	v_fmac_f32_e32 v144, v219, v219
	v_fmac_f32_e32 v144, v220, v220
	v_fmac_f32_e32 v144, v221, v221
	v_mul_f32_e32 v145, v222, v222
	v_fmac_f32_e32 v145, v223, v223
	v_fmac_f32_e32 v145, v224, v224
	v_fmac_f32_e32 v145, v225, v225
	v_fmac_f32_e32 v145, v226, v226
	v_fmac_f32_e32 v145, v227, v227
	v_fmac_f32_e32 v145, v228, v228
	v_fmac_f32_e32 v145, v229, v229
	v_lshlrev_b32_e32 v240, 16, v136
	v_and_b32_e32 v241, 0xffff0000, v136
	v_lshlrev_b32_e32 v242, 16, v137
	v_and_b32_e32 v243, 0xffff0000, v137
	v_lshlrev_b32_e32 v244, 16, v138
	v_and_b32_e32 v245, 0xffff0000, v138
	v_lshlrev_b32_e32 v246, 16, v139
	v_and_b32_e32 v247, 0xffff0000, v139
	v_lshlrev_b32_e32 v248, 16, v140
	v_and_b32_e32 v249, 0xffff0000, v140
	v_lshlrev_b32_e32 v250, 16, v141
	v_and_b32_e32 v251, 0xffff0000, v141
	v_lshlrev_b32_e32 v252, 16, v142
	v_and_b32_e32 v253, 0xffff0000, v142
	v_lshlrev_b32_e32 v254, 16, v143
	v_and_b32_e32 v255, 0xffff0000, v143
	s_nop 1
	v_add_f32_dpp v144, v144, v144 quad_perm:[1,0,3,2] row_mask:0xf bank_mask:0xf
	v_add_f32_dpp v145, v145, v145 quad_perm:[1,0,3,2] row_mask:0xf bank_mask:0xf
	s_nop 1
	v_add_f32_dpp v144, v144, v144 quad_perm:[2,3,0,1] row_mask:0xf bank_mask:0xf
	v_add_f32_dpp v145, v145, v145 quad_perm:[2,3,0,1] row_mask:0xf bank_mask:0xf
	s_nop 1
	v_add_f32_dpp v144, v144, v144 row_ror:4 row_mask:0xf bank_mask:0xf
	v_add_f32_dpp v145, v145, v145 row_ror:4 row_mask:0xf bank_mask:0xf
	s_nop 1
	v_add_f32_dpp v144, v144, v144 row_ror:8 row_mask:0xf bank_mask:0xf
	v_add_f32_dpp v145, v145, v145 row_ror:8 row_mask:0xf bank_mask:0xf
	v_fmamk_f32 v144, v144, 0x3c000000, v15
	v_fmamk_f32 v145, v145, 0x3c000000, v15
	v_rsq_f32_e32 v144, v144
	v_rsq_f32_e32 v145, v145
	v_mul_f32_e32 v148, 0xbfb8aa3b, v240
	v_mul_f32_e32 v149, 0xbfb8aa3b, v241
	v_mul_f32_e32 v150, 0xbfb8aa3b, v242
	v_mul_f32_e32 v151, 0xbfb8aa3b, v243
	v_mul_f32_e32 v4, 0xbfb8aa3b, v244
	v_mul_f32_e32 v5, 0xbfb8aa3b, v245
	v_mul_f32_e32 v6, 0xbfb8aa3b, v246
	v_mul_f32_e32 v7, 0xbfb8aa3b, v247
	v_exp_f32_e32 v148, v148
	v_exp_f32_e32 v149, v149
	v_exp_f32_e32 v150, v150
	v_exp_f32_e32 v151, v151
	v_exp_f32_e32 v4, v4
	v_exp_f32_e32 v5, v5
	v_exp_f32_e32 v6, v6
	v_exp_f32_e32 v7, v7
	v_add_f32_e32 v148, 1.0, v148
	v_add_f32_e32 v149, 1.0, v149
	v_add_f32_e32 v150, 1.0, v150
	v_add_f32_e32 v151, 1.0, v151
	v_add_f32_e32 v4, 1.0, v4
	v_add_f32_e32 v5, 1.0, v5
	v_add_f32_e32 v6, 1.0, v6
	v_add_f32_e32 v7, 1.0, v7
	v_rcp_f32_e32 v148, v148
	v_rcp_f32_e32 v149, v149
	v_rcp_f32_e32 v150, v150
	v_rcp_f32_e32 v151, v151
	v_rcp_f32_e32 v4, v4
	v_rcp_f32_e32 v5, v5
	v_rcp_f32_e32 v6, v6
	v_rcp_f32_e32 v7, v7
	v_mul_f32_e32 v240, v148, v240
	v_mul_f32_e32 v241, v149, v241
	v_mul_f32_e32 v242, v150, v242
	v_mul_f32_e32 v243, v151, v243
	v_mul_f32_e32 v244, v4, v244
	v_mul_f32_e32 v245, v5, v245
	v_mul_f32_e32 v246, v6, v246
	v_mul_f32_e32 v247, v7, v247
	v_mul_f32_e32 v148, 0xbfb8aa3b, v248
	v_mul_f32_e32 v149, 0xbfb8aa3b, v249
	v_mul_f32_e32 v150, 0xbfb8aa3b, v250
	v_mul_f32_e32 v151, 0xbfb8aa3b, v251
	v_mul_f32_e32 v4, 0xbfb8aa3b, v252
	v_mul_f32_e32 v5, 0xbfb8aa3b, v253
	v_mul_f32_e32 v6, 0xbfb8aa3b, v254
	v_mul_f32_e32 v7, 0xbfb8aa3b, v255
	v_exp_f32_e32 v148, v148
	v_exp_f32_e32 v149, v149
	v_exp_f32_e32 v150, v150
	v_exp_f32_e32 v151, v151
	v_exp_f32_e32 v4, v4
	v_exp_f32_e32 v5, v5
	v_exp_f32_e32 v6, v6
	v_exp_f32_e32 v7, v7
	v_add_f32_e32 v148, 1.0, v148
	v_add_f32_e32 v149, 1.0, v149
	v_add_f32_e32 v150, 1.0, v150
	v_add_f32_e32 v151, 1.0, v151
	v_add_f32_e32 v4, 1.0, v4
	v_add_f32_e32 v5, 1.0, v5
	v_add_f32_e32 v6, 1.0, v6
	v_add_f32_e32 v7, 1.0, v7
	v_rcp_f32_e32 v148, v148
	v_rcp_f32_e32 v149, v149
	v_rcp_f32_e32 v150, v150
	v_rcp_f32_e32 v151, v151
	v_rcp_f32_e32 v4, v4
	v_rcp_f32_e32 v5, v5
	v_rcp_f32_e32 v6, v6
	v_rcp_f32_e32 v7, v7
	v_mul_f32_e32 v248, v148, v248
	v_mul_f32_e32 v249, v149, v249
	v_mul_f32_e32 v250, v150, v250
	v_mul_f32_e32 v251, v151, v251
	v_mul_f32_e32 v252, v4, v252
	v_mul_f32_e32 v253, v5, v253
	v_mul_f32_e32 v254, v6, v254
	v_mul_f32_e32 v255, v7, v255
	v_mul_f32_e32 v214, v144, v214
	v_mul_f32_e32 v215, v144, v215
	v_mul_f32_e32 v216, v144, v216
	v_mul_f32_e32 v217, v144, v217
	v_mul_f32_e32 v218, v144, v218
	v_mul_f32_e32 v219, v144, v219
	v_mul_f32_e32 v220, v144, v220
	v_mul_f32_e32 v221, v144, v221
	v_mul_f32_e32 v222, v145, v222
	v_mul_f32_e32 v223, v145, v223
	v_mul_f32_e32 v224, v145, v224
	v_mul_f32_e32 v225, v145, v225
	v_mul_f32_e32 v226, v145, v226
	v_mul_f32_e32 v227, v145, v227
	v_mul_f32_e32 v228, v145, v228
	v_mul_f32_e32 v229, v145, v229
	v_mul_f32_e32 v214, v16, v214
	v_mul_f32_e32 v215, v17, v215
	v_mul_f32_e32 v216, v18, v216
	v_mul_f32_e32 v217, v19, v217
	v_mul_f32_e32 v218, v20, v218
	v_mul_f32_e32 v219, v21, v219
	v_mul_f32_e32 v220, v22, v220
	v_mul_f32_e32 v221, v23, v221
	v_mul_f32_e32 v222, v24, v222
	v_mul_f32_e32 v223, v25, v223
	v_mul_f32_e32 v224, v26, v224
	v_mul_f32_e32 v225, v27, v225
	v_mul_f32_e32 v226, v28, v226
	v_mul_f32_e32 v227, v29, v227
	v_mul_f32_e32 v228, v30, v228
	v_mul_f32_e32 v229, v31, v229
	v_mul_f32_e32 v214, v240, v214
	v_mul_f32_e32 v215, v241, v215
	v_mul_f32_e32 v216, v242, v216
	v_mul_f32_e32 v217, v243, v217
	v_mul_f32_e32 v218, v244, v218
	v_mul_f32_e32 v219, v245, v219
	v_mul_f32_e32 v220, v246, v220
	v_mul_f32_e32 v221, v247, v221
	v_mul_f32_e32 v222, v248, v222
	v_mul_f32_e32 v223, v249, v223
	v_mul_f32_e32 v224, v250, v224
	v_mul_f32_e32 v225, v251, v225
	v_mul_f32_e32 v226, v252, v226
	v_mul_f32_e32 v227, v253, v227
	v_mul_f32_e32 v228, v254, v228
	v_mul_f32_e32 v229, v255, v229
	v_cvt_pk_bf16_f32 v144, v214, v215
	v_cvt_pk_bf16_f32 v145, v216, v217
	v_cvt_pk_bf16_f32 v146, v218, v219
	v_cvt_pk_bf16_f32 v147, v220, v221
	v_cvt_pk_bf16_f32 v148, v222, v223
	v_cvt_pk_bf16_f32 v149, v224, v225
	v_cvt_pk_bf16_f32 v150, v226, v227
	v_cvt_pk_bf16_f32 v151, v228, v229
	s_mul_i32 s9, s46, 6
	s_add_i32 s9, s9, s8
	s_lshl_b32 s3, s9, 11
	s_add_u32 s24, s16, s3
	s_addc_u32 s25, s17, 0
	global_store_dwordx4 v2, v[144:147], s[24:25]
	global_store_dwordx4 v2, v[148:151], s[24:25] offset:1024
	s_waitcnt vmcnt(14)
; DI unsigned pk_bf16(float a, float b) { f32x2 v = {a, b}; bf2_t r = __builtin_convertvector(v, bf2_t); return __builtin_bit_cast(unsigned, r); }
; DI float bflo(unsigned u) { return __uint_as_float(u << 16); }
; DI float bfhi(unsigned u) { return __uint_as_float(u & 0xffff0000u); }
; DI float silu_f(float x) { return x * __builtin_amdgcn_rcpf(1.f + __expf(-x)); }
; DI void phase_gdn_gate(const Params& p) {
;     ...
;         const u32x4 z0 = *(const u32x4*)(P0 + (size_t)tok * LDP0 + 3072 + 16 * lane), z1 = *(const u32x4*)(P0 + (size_t)tok * LDP0 + 3072 + 16 * lane + 8);
;         float o[16], z[16];
;         const unsigned au[8] = {a0.x, a0.y, a0.z, a0.w, a1.x, a1.y, a1.z, a1.w}, zu[8] = {z0.x, z0.y, z0.z, z0.w, z1.x, z1.y, z1.z, z1.w};
;         float ss = 0.f;
; #pragma unroll
;         for (int i = 0; i < 8; ++i) { o[2 * i] = bflo(au[i]); o[2 * i + 1] = bfhi(au[i]); z[2 * i] = bflo(zu[i]); z[2 * i + 1] = bfhi(zu[i]); ss += o[2 * i] * o[2 * i] + o[2 * i + 1] * o[2 * i + 1]; }
;         ss += __shfl_xor(ss, 1); ss += __shfl_xor(ss, 2); ss += __shfl_xor(ss, 4);
;         const float rstd = rsqrtf(ss * (1.f / 128.f) + 1e-6f);
;         const int d0 = (16 * lane) & 127;
;         unsigned r[8];
; #pragma unroll
;         for (int i = 0; i < 8; ++i) { const float v0 = o[2 * i] * rstd * p.onorm_a[d0 + 2 * i] * silu_f(z[2 * i]), v1 = o[2 * i + 1] * rstd * p.onorm_a[d0 + 2 * i + 1] * silu_f(z[2 * i + 1]); r[i] = pk_bf16(v0, v1); }
;         *(u32x4*)(og + (size_t)tok * 1024 + 16 * lane) = (u32x4){r[0], r[1], r[2], r[3]};
;         *(u32x4*)(og + (size_t)tok * 1024 + 16 * lane + 8) = (u32x4){r[4], r[5], r[6], r[7]};
	v_lshlrev_b32_e32 v214, 16, v168
	v_and_b32_e32 v215, 0xffff0000, v168
	v_lshlrev_b32_e32 v216, 16, v169
	v_and_b32_e32 v217, 0xffff0000, v169
	v_lshlrev_b32_e32 v218, 16, v170
	v_and_b32_e32 v219, 0xffff0000, v170
	v_lshlrev_b32_e32 v220, 16, v171
	v_and_b32_e32 v221, 0xffff0000, v171
	v_lshlrev_b32_e32 v222, 16, v172
	v_and_b32_e32 v223, 0xffff0000, v172
	v_lshlrev_b32_e32 v224, 16, v173
	v_and_b32_e32 v225, 0xffff0000, v173
	v_lshlrev_b32_e32 v226, 16, v174
	v_and_b32_e32 v227, 0xffff0000, v174
	v_lshlrev_b32_e32 v228, 16, v175
	v_and_b32_e32 v229, 0xffff0000, v175
	v_mul_f32_e32 v144, v214, v214
	v_fmac_f32_e32 v144, v215, v215
	v_fmac_f32_e32 v144, v216, v216
	v_fmac_f32_e32 v144, v217, v217
	v_fmac_f32_e32 v144, v218, v218
	v_fmac_f32_e32 v144, v219, v219
	v_fmac_f32_e32 v144, v220, v220
	v_fmac_f32_e32 v144, v221, v221
	v_mul_f32_e32 v145, v222, v222
	v_fmac_f32_e32 v145, v223, v223
	v_fmac_f32_e32 v145, v224, v224
	v_fmac_f32_e32 v145, v225, v225
	v_fmac_f32_e32 v145, v226, v226
	v_fmac_f32_e32 v145, v227, v227
	v_fmac_f32_e32 v145, v228, v228
	v_fmac_f32_e32 v145, v229, v229
	v_lshlrev_b32_e32 v240, 16, v176
	v_and_b32_e32 v241, 0xffff0000, v176
	v_lshlrev_b32_e32 v242, 16, v177
	v_and_b32_e32 v243, 0xffff0000, v177
	v_lshlrev_b32_e32 v244, 16, v178
	v_and_b32_e32 v245, 0xffff0000, v178
	v_lshlrev_b32_e32 v246, 16, v179
	v_and_b32_e32 v247, 0xffff0000, v179
	v_lshlrev_b32_e32 v248, 16, v180
	v_and_b32_e32 v249, 0xffff0000, v180
	v_lshlrev_b32_e32 v250, 16, v181
	v_and_b32_e32 v251, 0xffff0000, v181
	v_lshlrev_b32_e32 v252, 16, v182
	v_and_b32_e32 v253, 0xffff0000, v182
	v_lshlrev_b32_e32 v254, 16, v183
	v_and_b32_e32 v255, 0xffff0000, v183
	s_nop 1
	v_add_f32_dpp v144, v144, v144 quad_perm:[1,0,3,2] row_mask:0xf bank_mask:0xf
	v_add_f32_dpp v145, v145, v145 quad_perm:[1,0,3,2] row_mask:0xf bank_mask:0xf
	s_nop 1
	v_add_f32_dpp v144, v144, v144 quad_perm:[2,3,0,1] row_mask:0xf bank_mask:0xf
	v_add_f32_dpp v145, v145, v145 quad_perm:[2,3,0,1] row_mask:0xf bank_mask:0xf
	s_nop 1
	v_add_f32_dpp v144, v144, v144 row_ror:4 row_mask:0xf bank_mask:0xf
	v_add_f32_dpp v145, v145, v145 row_ror:4 row_mask:0xf bank_mask:0xf
	s_nop 1
	v_add_f32_dpp v144, v144, v144 row_ror:8 row_mask:0xf bank_mask:0xf
	v_add_f32_dpp v145, v145, v145 row_ror:8 row_mask:0xf bank_mask:0xf
	v_fmamk_f32 v144, v144, 0x3c000000, v15
	v_fmamk_f32 v145, v145, 0x3c000000, v15
	v_rsq_f32_e32 v144, v144
	v_rsq_f32_e32 v145, v145
	v_mul_f32_e32 v148, 0xbfb8aa3b, v240
	v_mul_f32_e32 v149, 0xbfb8aa3b, v241
	v_mul_f32_e32 v150, 0xbfb8aa3b, v242
	v_mul_f32_e32 v151, 0xbfb8aa3b, v243
	v_mul_f32_e32 v4, 0xbfb8aa3b, v244
	v_mul_f32_e32 v5, 0xbfb8aa3b, v245
	v_mul_f32_e32 v6, 0xbfb8aa3b, v246
	v_mul_f32_e32 v7, 0xbfb8aa3b, v247
	v_exp_f32_e32 v148, v148
	v_exp_f32_e32 v149, v149
	v_exp_f32_e32 v150, v150
	v_exp_f32_e32 v151, v151
	v_exp_f32_e32 v4, v4
	v_exp_f32_e32 v5, v5
	v_exp_f32_e32 v6, v6
	v_exp_f32_e32 v7, v7
	v_add_f32_e32 v148, 1.0, v148
	v_add_f32_e32 v149, 1.0, v149
	v_add_f32_e32 v150, 1.0, v150
	v_add_f32_e32 v151, 1.0, v151
	v_add_f32_e32 v4, 1.0, v4
	v_add_f32_e32 v5, 1.0, v5
	v_add_f32_e32 v6, 1.0, v6
	v_add_f32_e32 v7, 1.0, v7
	v_rcp_f32_e32 v148, v148
	v_rcp_f32_e32 v149, v149
	v_rcp_f32_e32 v150, v150
	v_rcp_f32_e32 v151, v151
	v_rcp_f32_e32 v4, v4
	v_rcp_f32_e32 v5, v5
	v_rcp_f32_e32 v6, v6
	v_rcp_f32_e32 v7, v7
	v_mul_f32_e32 v240, v148, v240
	v_mul_f32_e32 v241, v149, v241
	v_mul_f32_e32 v242, v150, v242
	v_mul_f32_e32 v243, v151, v243
	v_mul_f32_e32 v244, v4, v244
	v_mul_f32_e32 v245, v5, v245
	v_mul_f32_e32 v246, v6, v246
	v_mul_f32_e32 v247, v7, v247
	v_mul_f32_e32 v148, 0xbfb8aa3b, v248
	v_mul_f32_e32 v149, 0xbfb8aa3b, v249
	v_mul_f32_e32 v150, 0xbfb8aa3b, v250
	v_mul_f32_e32 v151, 0xbfb8aa3b, v251
	v_mul_f32_e32 v4, 0xbfb8aa3b, v252
	v_mul_f32_e32 v5, 0xbfb8aa3b, v253
	v_mul_f32_e32 v6, 0xbfb8aa3b, v254
	v_mul_f32_e32 v7, 0xbfb8aa3b, v255
	v_exp_f32_e32 v148, v148
	v_exp_f32_e32 v149, v149
	v_exp_f32_e32 v150, v150
	v_exp_f32_e32 v151, v151
	v_exp_f32_e32 v4, v4
	v_exp_f32_e32 v5, v5
	v_exp_f32_e32 v6, v6
	v_exp_f32_e32 v7, v7
	v_add_f32_e32 v148, 1.0, v148
	v_add_f32_e32 v149, 1.0, v149
	v_add_f32_e32 v150, 1.0, v150
	v_add_f32_e32 v151, 1.0, v151
	v_add_f32_e32 v4, 1.0, v4
	v_add_f32_e32 v5, 1.0, v5
	v_add_f32_e32 v6, 1.0, v6
	v_add_f32_e32 v7, 1.0, v7
	v_rcp_f32_e32 v148, v148
	v_rcp_f32_e32 v149, v149
	v_rcp_f32_e32 v150, v150
	v_rcp_f32_e32 v151, v151
	v_rcp_f32_e32 v4, v4
	v_rcp_f32_e32 v5, v5
	v_rcp_f32_e32 v6, v6
	v_rcp_f32_e32 v7, v7
	v_mul_f32_e32 v248, v148, v248
	v_mul_f32_e32 v249, v149, v249
	v_mul_f32_e32 v250, v150, v250
	v_mul_f32_e32 v251, v151, v251
	v_mul_f32_e32 v252, v4, v252
	v_mul_f32_e32 v253, v5, v253
	v_mul_f32_e32 v254, v6, v254
	v_mul_f32_e32 v255, v7, v255
	v_mul_f32_e32 v214, v144, v214
	v_mul_f32_e32 v215, v144, v215
	v_mul_f32_e32 v216, v144, v216
	v_mul_f32_e32 v217, v144, v217
	v_mul_f32_e32 v218, v144, v218
	v_mul_f32_e32 v219, v144, v219
	v_mul_f32_e32 v220, v144, v220
	v_mul_f32_e32 v221, v144, v221
	v_mul_f32_e32 v222, v145, v222
	v_mul_f32_e32 v223, v145, v223
	v_mul_f32_e32 v224, v145, v224
	v_mul_f32_e32 v225, v145, v225
	v_mul_f32_e32 v226, v145, v226
	v_mul_f32_e32 v227, v145, v227
	v_mul_f32_e32 v228, v145, v228
	v_mul_f32_e32 v229, v145, v229
	v_mul_f32_e32 v214, v16, v214
	v_mul_f32_e32 v215, v17, v215
	v_mul_f32_e32 v216, v18, v216
	v_mul_f32_e32 v217, v19, v217
	v_mul_f32_e32 v218, v20, v218
	v_mul_f32_e32 v219, v21, v219
	v_mul_f32_e32 v220, v22, v220
	v_mul_f32_e32 v221, v23, v221
	v_mul_f32_e32 v222, v24, v222
	v_mul_f32_e32 v223, v25, v223
	v_mul_f32_e32 v224, v26, v224
	v_mul_f32_e32 v225, v27, v225
	v_mul_f32_e32 v226, v28, v226
	v_mul_f32_e32 v227, v29, v227
	v_mul_f32_e32 v228, v30, v228
	v_mul_f32_e32 v229, v31, v229
	v_mul_f32_e32 v214, v240, v214
	v_mul_f32_e32 v215, v241, v215
	v_mul_f32_e32 v216, v242, v216
	v_mul_f32_e32 v217, v243, v217
	v_mul_f32_e32 v218, v244, v218
	v_mul_f32_e32 v219, v245, v219
	v_mul_f32_e32 v220, v246, v220
	v_mul_f32_e32 v221, v247, v221
	v_mul_f32_e32 v222, v248, v222
	v_mul_f32_e32 v223, v249, v223
	v_mul_f32_e32 v224, v250, v224
	v_mul_f32_e32 v225, v251, v225
	v_mul_f32_e32 v226, v252, v226
	v_mul_f32_e32 v227, v253, v227
	v_mul_f32_e32 v228, v254, v228
	v_mul_f32_e32 v229, v255, v229
	v_cvt_pk_bf16_f32 v144, v214, v215
	v_cvt_pk_bf16_f32 v145, v216, v217
	v_cvt_pk_bf16_f32 v146, v218, v219
	v_cvt_pk_bf16_f32 v147, v220, v221
	v_cvt_pk_bf16_f32 v148, v222, v223
	v_cvt_pk_bf16_f32 v149, v224, v225
	v_cvt_pk_bf16_f32 v150, v226, v227
	v_cvt_pk_bf16_f32 v151, v228, v229
	s_mul_i32 s9, s46, 7
	s_add_i32 s9, s9, s8
	s_lshl_b32 s3, s9, 11
	s_add_u32 s24, s16, s3
	s_addc_u32 s25, s17, 0
	global_store_dwordx4 v2, v[144:147], s[24:25]
	global_store_dwordx4 v2, v[148:151], s[24:25] offset:1024
	s_cmpk_lt_u32 s8, 0x400
	s_cbranch_scc0 .Lg4_done
; DI unsigned pk_bf16(float a, float b) { f32x2 v = {a, b}; bf2_t r = __builtin_convertvector(v, bf2_t); return __builtin_bit_cast(unsigned, r); }
; DI float bflo(unsigned u) { return __uint_as_float(u << 16); }
; DI float bfhi(unsigned u) { return __uint_as_float(u & 0xffff0000u); }
; DI float silu_f(float x) { return x * __builtin_amdgcn_rcpf(1.f + __expf(-x)); }
; DI void phase_gdn_gate(const Params& p) {
;     ...
;         const u32x4 z0 = *(const u32x4*)(P0 + (size_t)tok * LDP0 + 3072 + 16 * lane), z1 = *(const u32x4*)(P0 + (size_t)tok * LDP0 + 3072 + 16 * lane + 8);
;         float o[16], z[16];
;         const unsigned au[8] = {a0.x, a0.y, a0.z, a0.w, a1.x, a1.y, a1.z, a1.w}, zu[8] = {z0.x, z0.y, z0.z, z0.w, z1.x, z1.y, z1.z, z1.w};
;         float ss = 0.f;
; #pragma unroll
;         for (int i = 0; i < 8; ++i) { o[2 * i] = bflo(au[i]); o[2 * i + 1] = bfhi(au[i]); z[2 * i] = bflo(zu[i]); z[2 * i + 1] = bfhi(zu[i]); ss += o[2 * i] * o[2 * i] + o[2 * i + 1] * o[2 * i + 1]; }
;         ss += __shfl_xor(ss, 1); ss += __shfl_xor(ss, 2); ss += __shfl_xor(ss, 4);
;         const float rstd = rsqrtf(ss * (1.f / 128.f) + 1e-6f);
;         const int d0 = (16 * lane) & 127;
;         unsigned r[8];
; #pragma unroll
;         for (int i = 0; i < 8; ++i) { const float v0 = o[2 * i] * rstd * p.onorm_a[d0 + 2 * i] * silu_f(z[2 * i]), v1 = o[2 * i + 1] * rstd * p.onorm_a[d0 + 2 * i + 1] * silu_f(z[2 * i + 1]); r[i] = pk_bf16(v0, v1); }
;         *(u32x4*)(og + (size_t)tok * 1024 + 16 * lane) = (u32x4){r[0], r[1], r[2], r[3]};
;         *(u32x4*)(og + (size_t)tok * 1024 + 16 * lane + 8) = (u32x4){r[4], r[5], r[6], r[7]};
	s_waitcnt vmcnt(16)
	v_lshlrev_b32_e32 v214, 16, v198
	v_and_b32_e32 v215, 0xffff0000, v198
	v_lshlrev_b32_e32 v216, 16, v199
	v_and_b32_e32 v217, 0xffff0000, v199
	v_lshlrev_b32_e32 v218, 16, v200
	v_and_b32_e32 v219, 0xffff0000, v200
	v_lshlrev_b32_e32 v220, 16, v201
	v_and_b32_e32 v221, 0xffff0000, v201
	v_lshlrev_b32_e32 v222, 16, v202
	v_and_b32_e32 v223, 0xffff0000, v202
	v_lshlrev_b32_e32 v224, 16, v203
	v_and_b32_e32 v225, 0xffff0000, v203
	v_lshlrev_b32_e32 v226, 16, v204
	v_and_b32_e32 v227, 0xffff0000, v204
	v_lshlrev_b32_e32 v228, 16, v205
	v_and_b32_e32 v229, 0xffff0000, v205
	v_mul_f32_e32 v144, v214, v214
	v_fmac_f32_e32 v144, v215, v215
	v_fmac_f32_e32 v144, v216, v216
	v_fmac_f32_e32 v144, v217, v217
	v_fmac_f32_e32 v144, v218, v218
	v_fmac_f32_e32 v144, v219, v219
	v_fmac_f32_e32 v144, v220, v220
	v_fmac_f32_e32 v144, v221, v221
	v_mul_f32_e32 v145, v222, v222
	v_fmac_f32_e32 v145, v223, v223
	v_fmac_f32_e32 v145, v224, v224
	v_fmac_f32_e32 v145, v225, v225
	v_fmac_f32_e32 v145, v226, v226
	v_fmac_f32_e32 v145, v227, v227
	v_fmac_f32_e32 v145, v228, v228
	v_fmac_f32_e32 v145, v229, v229
	v_lshlrev_b32_e32 v240, 16, v206
	v_and_b32_e32 v241, 0xffff0000, v206
	v_lshlrev_b32_e32 v242, 16, v207
	v_and_b32_e32 v243, 0xffff0000, v207
	v_lshlrev_b32_e32 v244, 16, v208
	v_and_b32_e32 v245, 0xffff0000, v208
	v_lshlrev_b32_e32 v246, 16, v209
	v_and_b32_e32 v247, 0xffff0000, v209
	v_lshlrev_b32_e32 v248, 16, v210
	v_and_b32_e32 v249, 0xffff0000, v210
	v_lshlrev_b32_e32 v250, 16, v211
	v_and_b32_e32 v251, 0xffff0000, v211
	v_lshlrev_b32_e32 v252, 16, v212
	v_and_b32_e32 v253, 0xffff0000, v212
	v_lshlrev_b32_e32 v254, 16, v213
	v_and_b32_e32 v255, 0xffff0000, v213
	s_nop 1
	v_add_f32_dpp v144, v144, v144 quad_perm:[1,0,3,2] row_mask:0xf bank_mask:0xf
	v_add_f32_dpp v145, v145, v145 quad_perm:[1,0,3,2] row_mask:0xf bank_mask:0xf
	s_nop 1
	v_add_f32_dpp v144, v144, v144 quad_perm:[2,3,0,1] row_mask:0xf bank_mask:0xf
	v_add_f32_dpp v145, v145, v145 quad_perm:[2,3,0,1] row_mask:0xf bank_mask:0xf
	s_nop 1
	v_add_f32_dpp v144, v144, v144 row_ror:4 row_mask:0xf bank_mask:0xf
	v_add_f32_dpp v145, v145, v145 row_ror:4 row_mask:0xf bank_mask:0xf
	s_nop 1
	v_add_f32_dpp v144, v144, v144 row_ror:8 row_mask:0xf bank_mask:0xf
	v_add_f32_dpp v145, v145, v145 row_ror:8 row_mask:0xf bank_mask:0xf
	v_fmamk_f32 v144, v144, 0x3c000000, v15
	v_fmamk_f32 v145, v145, 0x3c000000, v15
	v_rsq_f32_e32 v144, v144
	v_rsq_f32_e32 v145, v145
	v_mul_f32_e32 v148, 0xbfb8aa3b, v240
	v_mul_f32_e32 v149, 0xbfb8aa3b, v241
	v_mul_f32_e32 v150, 0xbfb8aa3b, v242
	v_mul_f32_e32 v151, 0xbfb8aa3b, v243
	v_mul_f32_e32 v4, 0xbfb8aa3b, v244
	v_mul_f32_e32 v5, 0xbfb8aa3b, v245
	v_mul_f32_e32 v6, 0xbfb8aa3b, v246
	v_mul_f32_e32 v7, 0xbfb8aa3b, v247
	v_exp_f32_e32 v148, v148
	v_exp_f32_e32 v149, v149
	v_exp_f32_e32 v150, v150
	v_exp_f32_e32 v151, v151
	v_exp_f32_e32 v4, v4
	v_exp_f32_e32 v5, v5
	v_exp_f32_e32 v6, v6
	v_exp_f32_e32 v7, v7
	v_add_f32_e32 v148, 1.0, v148
	v_add_f32_e32 v149, 1.0, v149
	v_add_f32_e32 v150, 1.0, v150
	v_add_f32_e32 v151, 1.0, v151
	v_add_f32_e32 v4, 1.0, v4
	v_add_f32_e32 v5, 1.0, v5
	v_add_f32_e32 v6, 1.0, v6
	v_add_f32_e32 v7, 1.0, v7
	v_rcp_f32_e32 v148, v148
	v_rcp_f32_e32 v149, v149
	v_rcp_f32_e32 v150, v150
	v_rcp_f32_e32 v151, v151
	v_rcp_f32_e32 v4, v4
	v_rcp_f32_e32 v5, v5
	v_rcp_f32_e32 v6, v6
	v_rcp_f32_e32 v7, v7
	v_mul_f32_e32 v240, v148, v240
	v_mul_f32_e32 v241, v149, v241
	v_mul_f32_e32 v242, v150, v242
	v_mul_f32_e32 v243, v151, v243
	v_mul_f32_e32 v244, v4, v244
	v_mul_f32_e32 v245, v5, v245
	v_mul_f32_e32 v246, v6, v246
	v_mul_f32_e32 v247, v7, v247
	v_mul_f32_e32 v148, 0xbfb8aa3b, v248
	v_mul_f32_e32 v149, 0xbfb8aa3b, v249
	v_mul_f32_e32 v150, 0xbfb8aa3b, v250
	v_mul_f32_e32 v151, 0xbfb8aa3b, v251
	v_mul_f32_e32 v4, 0xbfb8aa3b, v252
	v_mul_f32_e32 v5, 0xbfb8aa3b, v253
	v_mul_f32_e32 v6, 0xbfb8aa3b, v254
	v_mul_f32_e32 v7, 0xbfb8aa3b, v255
	v_exp_f32_e32 v148, v148
	v_exp_f32_e32 v149, v149
	v_exp_f32_e32 v150, v150
	v_exp_f32_e32 v151, v151
	v_exp_f32_e32 v4, v4
	v_exp_f32_e32 v5, v5
	v_exp_f32_e32 v6, v6
	v_exp_f32_e32 v7, v7
	v_add_f32_e32 v148, 1.0, v148
	v_add_f32_e32 v149, 1.0, v149
	v_add_f32_e32 v150, 1.0, v150
	v_add_f32_e32 v151, 1.0, v151
	v_add_f32_e32 v4, 1.0, v4
	v_add_f32_e32 v5, 1.0, v5
	v_add_f32_e32 v6, 1.0, v6
	v_add_f32_e32 v7, 1.0, v7
	v_rcp_f32_e32 v148, v148
	v_rcp_f32_e32 v149, v149
	v_rcp_f32_e32 v150, v150
	v_rcp_f32_e32 v151, v151
	v_rcp_f32_e32 v4, v4
	v_rcp_f32_e32 v5, v5
	v_rcp_f32_e32 v6, v6
	v_rcp_f32_e32 v7, v7
	v_mul_f32_e32 v248, v148, v248
	v_mul_f32_e32 v249, v149, v249
	v_mul_f32_e32 v250, v150, v250
	v_mul_f32_e32 v251, v151, v251
	v_mul_f32_e32 v252, v4, v252
	v_mul_f32_e32 v253, v5, v253
	v_mul_f32_e32 v254, v6, v254
	v_mul_f32_e32 v255, v7, v255
	v_mul_f32_e32 v214, v144, v214
	v_mul_f32_e32 v215, v144, v215
	v_mul_f32_e32 v216, v144, v216
	v_mul_f32_e32 v217, v144, v217
	v_mul_f32_e32 v218, v144, v218
	v_mul_f32_e32 v219, v144, v219
	v_mul_f32_e32 v220, v144, v220
	v_mul_f32_e32 v221, v144, v221
	v_mul_f32_e32 v222, v145, v222
	v_mul_f32_e32 v223, v145, v223
	v_mul_f32_e32 v224, v145, v224
	v_mul_f32_e32 v225, v145, v225
	v_mul_f32_e32 v226, v145, v226
	v_mul_f32_e32 v227, v145, v227
	v_mul_f32_e32 v228, v145, v228
	v_mul_f32_e32 v229, v145, v229
	v_mul_f32_e32 v214, v16, v214
	v_mul_f32_e32 v215, v17, v215
	v_mul_f32_e32 v216, v18, v216
	v_mul_f32_e32 v217, v19, v217
	v_mul_f32_e32 v218, v20, v218
	v_mul_f32_e32 v219, v21, v219
	v_mul_f32_e32 v220, v22, v220
	v_mul_f32_e32 v221, v23, v221
	v_mul_f32_e32 v222, v24, v222
	v_mul_f32_e32 v223, v25, v223
	v_mul_f32_e32 v224, v26, v224
	v_mul_f32_e32 v225, v27, v225
	v_mul_f32_e32 v226, v28, v226
	v_mul_f32_e32 v227, v29, v227
	v_mul_f32_e32 v228, v30, v228
	v_mul_f32_e32 v229, v31, v229
	v_mul_f32_e32 v214, v240, v214
	v_mul_f32_e32 v215, v241, v215
	v_mul_f32_e32 v216, v242, v216
	v_mul_f32_e32 v217, v243, v217
	v_mul_f32_e32 v218, v244, v218
	v_mul_f32_e32 v219, v245, v219
	v_mul_f32_e32 v220, v246, v220
	v_mul_f32_e32 v221, v247, v221
	v_mul_f32_e32 v222, v248, v222
	v_mul_f32_e32 v223, v249, v223
	v_mul_f32_e32 v224, v250, v224
	v_mul_f32_e32 v225, v251, v225
	v_mul_f32_e32 v226, v252, v226
	v_mul_f32_e32 v227, v253, v227
	v_mul_f32_e32 v228, v254, v228
	v_mul_f32_e32 v229, v255, v229
	v_cvt_pk_bf16_f32 v144, v214, v215
	v_cvt_pk_bf16_f32 v145, v216, v217
	v_cvt_pk_bf16_f32 v146, v218, v219
	v_cvt_pk_bf16_f32 v147, v220, v221
	v_cvt_pk_bf16_f32 v148, v222, v223
	v_cvt_pk_bf16_f32 v149, v224, v225
	v_cvt_pk_bf16_f32 v150, v226, v227
	v_cvt_pk_bf16_f32 v151, v228, v229
	s_mul_i32 s9, s46, 8
	s_add_i32 s9, s9, s8
	s_lshl_b32 s3, s9, 11
	s_add_u32 s24, s16, s3
	s_addc_u32 s25, s17, 0
	global_store_dwordx4 v2, v[144:147], s[24:25]
	global_store_dwordx4 v2, v[148:151], s[24:25] offset:1024
